# baseline (speedup 1.0000x reference)
;   #define LDA(dst,b,h) for(int m=0;m<4;++m)for(int k=0;k<2;++k) \
;     dst[m][k]=*reinterpret_cast<const bf16x8*>((char*)SA(b,h)+lds_byte(wr*64+m*16+fr,k*32+fq*8))
;   #define LDB(dst,b,h) for(int n=0;n<2;++n)for(int k=0;k<2;++k) \
;     dst[n][k]=*reinterpret_cast<const bf16x8*>((char*)SB(b,h)+lds_byte(wc*32+n*16+fr,k*32+fq*8))
;   #define MMA(ai,bj,At,Bt_) do{__builtin_amdgcn_s_setprio(1); \
;     for(int m=0;m<4;++m)for(int n=0;n<2;++n)for(int k=0;k<2;++k) \
;       acc[ai][bj][m][n]=__builtin_amdgcn_mfma_f32_16x16x32_bf16(Bt_[n][k],At[m][k],acc[ai][bj][m][n],0,0,0); \
;     __builtin_amdgcn_s_setprio(0);}while(0)
;   #define WAIT_V(n) asm volatile("s_waitcnt vmcnt(" #n ")":::"memory")
;   #define WAIT_L(n) asm volatile("s_waitcnt lgkmcnt(" #n ")":::"memory")
;   #define BAR __builtin_amdgcn_s_barrier()
;   #define SCHED __builtin_amdgcn_sched_barrier(0)
; template <bool TWO, class MID> ...
;     ...
;   for(int t=0;t<nt-2;t+=2){
;     if (TWO && t == nt1) mid();
;     LDB(B0,0,0); SCHED; LDA(At,0,0); STAGE_A(SA(1,1),1,t+1);
;     WAIT_L(8); BAR; WAIT_L(0); MMA(0,0,At,B0); BAR; SCHED;
;     LDB(B1,0,1); STAGE_B(SB(0,0),0,t+2);
;     BAR; WAIT_L(0); MMA(0,1,At,B1); BAR;
;     LDA(At,0,1); STAGE_A(SA(0,0),0,t+2);
;     BAR; WAIT_L(0); MMA(1,0,At,B0); BAR; SCHED;
;     STAGE_B(SB(0,1),1,t+2);
;     WAIT_V(6); BAR; MMA(1,1,At,B1); BAR;
.LBB0_169:
	ds_read_b128 v[170:173], v143
	ds_read_b128 v[174:177], v143 offset:1024
	ds_read_b128 v[178:181], v143 offset:2048
	ds_read_b128 v[182:185], v143 offset:3072
	ds_read_b128 v[186:189], v168
	ds_read_b128 v[190:193], v168 offset:1024
	ds_read_b128 v[196:199], v167
	ds_read_b128 v[200:203], v167 offset:1024
	ds_read_b128 v[204:207], v166
	ds_read_b128 v[208:211], v166 offset:1024
	ds_read_b128 v[212:215], v147
	ds_read_b128 v[216:219], v147 offset:1024
	s_add_u32 s17, s0, s12
	s_addc_u32 s18, s1, s13
	s_add_u32 s20, s17, 0x8080080
	s_addc_u32 s21, s18, 0
	s_add_u32 m0, s98, 0xc000
	global_load_lds_dwordx4 v132, s[20:21]
	s_add_u32 m0, s98, 0xe000
	global_load_lds_dwordx4 v130, s[20:21]
	s_waitcnt lgkmcnt(8)
	s_setprio 1
	s_barrier
	s_waitcnt lgkmcnt(0)
	v_mfma_f32_16x16x32_bf16 v[126:129], v[170:173], v[186:189], v[126:129]
	v_mfma_f32_16x16x32_bf16 v[122:125], v[178:181], v[186:189], v[122:125]
	v_mfma_f32_16x16x32_bf16 v[118:121], v[170:173], v[196:199], v[118:121]
	v_mfma_f32_16x16x32_bf16 v[114:117], v[178:181], v[196:199], v[114:117]
	v_mfma_f32_16x16x32_bf16 v[110:113], v[170:173], v[204:207], v[110:113]
	v_mfma_f32_16x16x32_bf16 v[106:109], v[178:181], v[204:207], v[106:109]
	v_mfma_f32_16x16x32_bf16 v[102:105], v[170:173], v[212:215], v[102:105]
	v_mfma_f32_16x16x32_bf16 v[98:101], v[178:181], v[212:215], v[98:101]
	v_mfma_f32_16x16x32_bf16 v[126:129], v[174:177], v[190:193], v[126:129]
	v_mfma_f32_16x16x32_bf16 v[122:125], v[182:185], v[190:193], v[122:125]
	v_mfma_f32_16x16x32_bf16 v[118:121], v[174:177], v[200:203], v[118:121]
	v_mfma_f32_16x16x32_bf16 v[114:117], v[182:185], v[200:203], v[114:117]
	v_mfma_f32_16x16x32_bf16 v[110:113], v[174:177], v[208:211], v[110:113]
	v_mfma_f32_16x16x32_bf16 v[106:109], v[182:185], v[208:211], v[106:109]
	v_mfma_f32_16x16x32_bf16 v[102:105], v[174:177], v[216:219], v[102:105]
	v_mfma_f32_16x16x32_bf16 v[98:101], v[182:185], v[216:219], v[98:101]
	s_barrier
	s_setprio 0
	s_add_u32 s19, s0, s14
	ds_read_b128 v[220:223], v141
	ds_read_b128 v[224:227], v141 offset:1024
	ds_read_b128 v[228:231], v141 offset:2048
	ds_read_b128 v[232:235], v141 offset:3072
	s_addc_u32 s20, s1, s15
	s_add_u32 s26, s19, 0x100
	s_addc_u32 s27, s20, 0
	s_add_u32 m0, s98, 0x10000
	global_load_lds_dwordx4 v132, s[26:27]
	s_add_u32 m0, s98, 0x12000
	global_load_lds_dwordx4 v130, s[26:27]
	s_setprio 1
	s_barrier
	s_waitcnt lgkmcnt(0)
	v_mfma_f32_16x16x32_bf16 v[94:97], v[220:223], v[186:189], v[94:97]
	v_mfma_f32_16x16x32_bf16 v[90:93], v[228:231], v[186:189], v[90:93]
	v_mfma_f32_16x16x32_bf16 v[86:89], v[220:223], v[196:199], v[86:89]
	v_mfma_f32_16x16x32_bf16 v[82:85], v[228:231], v[196:199], v[82:85]
	v_mfma_f32_16x16x32_bf16 v[78:81], v[220:223], v[204:207], v[78:81]
	v_mfma_f32_16x16x32_bf16 v[74:77], v[228:231], v[204:207], v[74:77]
	v_mfma_f32_16x16x32_bf16 v[70:73], v[220:223], v[212:215], v[70:73]
	v_mfma_f32_16x16x32_bf16 v[66:69], v[228:231], v[212:215], v[66:69]
	v_mfma_f32_16x16x32_bf16 v[94:97], v[224:227], v[190:193], v[94:97]
	v_mfma_f32_16x16x32_bf16 v[90:93], v[232:235], v[190:193], v[90:93]
	v_mfma_f32_16x16x32_bf16 v[86:89], v[224:227], v[200:203], v[86:89]
	v_mfma_f32_16x16x32_bf16 v[82:85], v[232:235], v[200:203], v[82:85]
	v_mfma_f32_16x16x32_bf16 v[78:81], v[224:227], v[208:211], v[78:81]
	v_mfma_f32_16x16x32_bf16 v[74:77], v[232:235], v[208:211], v[74:77]
	v_mfma_f32_16x16x32_bf16 v[70:73], v[224:227], v[216:219], v[70:73]
	v_mfma_f32_16x16x32_bf16 v[66:69], v[232:235], v[216:219], v[66:69]
	s_barrier
	s_setprio 0
	ds_read_b128 v[186:189], v168 offset:16384
	ds_read_b128 v[190:193], v168 offset:17408
	ds_read_b128 v[196:199], v167 offset:16384
	ds_read_b128 v[200:203], v167 offset:17408
	ds_read_b128 v[204:207], v166 offset:16384
	ds_read_b128 v[208:211], v166 offset:17408
	ds_read_b128 v[212:215], v147 offset:16384
	ds_read_b128 v[216:219], v147 offset:17408
	s_add_u32 s26, s17, 0x8000100
	s_addc_u32 s27, s18, 0
	s_add_u32 m0, s98, 0x0
	global_load_lds_dwordx4 v132, s[26:27]
	s_add_u32 m0, s98, 0x2000
	global_load_lds_dwordx4 v130, s[26:27]
	s_setprio 1
	s_barrier
	s_waitcnt lgkmcnt(0)
	v_mfma_f32_16x16x32_bf16 v[62:65], v[170:173], v[186:189], v[62:65]
	v_mfma_f32_16x16x32_bf16 v[58:61], v[178:181], v[186:189], v[58:61]
	v_mfma_f32_16x16x32_bf16 v[54:57], v[170:173], v[196:199], v[54:57]
	v_mfma_f32_16x16x32_bf16 v[50:53], v[178:181], v[196:199], v[50:53]
	v_mfma_f32_16x16x32_bf16 v[46:49], v[170:173], v[204:207], v[46:49]
	v_mfma_f32_16x16x32_bf16 v[42:45], v[178:181], v[204:207], v[42:45]
	v_mfma_f32_16x16x32_bf16 v[38:41], v[170:173], v[212:215], v[38:41]
	v_mfma_f32_16x16x32_bf16 v[34:37], v[178:181], v[212:215], v[34:37]
	v_mfma_f32_16x16x32_bf16 v[62:65], v[174:177], v[190:193], v[62:65]
	v_mfma_f32_16x16x32_bf16 v[58:61], v[182:185], v[190:193], v[58:61]
	v_mfma_f32_16x16x32_bf16 v[54:57], v[174:177], v[200:203], v[54:57]
	v_mfma_f32_16x16x32_bf16 v[50:53], v[182:185], v[200:203], v[50:53]
	v_mfma_f32_16x16x32_bf16 v[46:49], v[174:177], v[208:211], v[46:49]
	v_mfma_f32_16x16x32_bf16 v[42:45], v[182:185], v[208:211], v[42:45]
	v_mfma_f32_16x16x32_bf16 v[38:41], v[174:177], v[216:219], v[38:41]
	v_mfma_f32_16x16x32_bf16 v[34:37], v[182:185], v[216:219], v[34:37]
	s_barrier
	s_setprio 0
	s_add_u32 s26, s19, 0x80100
	s_addc_u32 s27, s20, 0
	s_add_u32 m0, s98, 0x14000
	global_load_lds_dwordx4 v132, s[26:27]
	s_add_u32 m0, s98, 0x16000
	global_load_lds_dwordx4 v130, s[26:27]
	s_waitcnt vmcnt(6)
	s_setprio 1
	s_barrier
;   #define LDA(dst,b,h) for(int m=0;m<4;++m)for(int k=0;k<2;++k) \
;     dst[m][k]=*reinterpret_cast<const bf16x8*>((char*)SA(b,h)+lds_byte(wr*64+m*16+fr,k*32+fq*8))
;   #define LDB(dst,b,h) for(int n=0;n<2;++n)for(int k=0;k<2;++k) \
;     dst[n][k]=*reinterpret_cast<const bf16x8*>((char*)SB(b,h)+lds_byte(wc*32+n*16+fr,k*32+fq*8))
;   #define MMA(ai,bj,At,Bt_) do{__builtin_amdgcn_s_setprio(1); \
;     for(int m=0;m<4;++m)for(int n=0;n<2;++n)for(int k=0;k<2;++k) \
;       acc[ai][bj][m][n]=__builtin_amdgcn_mfma_f32_16x16x32_bf16(Bt_[n][k],At[m][k],acc[ai][bj][m][n],0,0,0); \
;     __builtin_amdgcn_s_setprio(0);}while(0)
;   #define WAIT_V(n) asm volatile("s_waitcnt vmcnt(" #n ")":::"memory")
;   #define WAIT_L(n) asm volatile("s_waitcnt lgkmcnt(" #n ")":::"memory")
;   #define BAR __builtin_amdgcn_s_barrier()
;   #define SCHED __builtin_amdgcn_sched_barrier(0)
; template <bool TWO, class MID> ...
;     ...
;     WAIT_V(6); BAR; MMA(1,1,At,B1); BAR;
;     LDB(B0,1,0); SCHED; LDA(At,1,0); STAGE_A(SA(0,1),1,t+2);
;     WAIT_L(8); BAR; WAIT_L(0); MMA(0,0,At,B0); BAR; SCHED;
;     LDB(B1,1,1); STAGE_B(SB(1,0),0,t+3);
;     BAR; WAIT_L(0); MMA(0,1,At,B1); BAR;
;     LDA(At,1,1); STAGE_A(SA(1,0),0,t+3);
;     BAR; WAIT_L(0); MMA(1,0,At,B0); BAR; SCHED;
	v_mfma_f32_16x16x32_bf16 v[30:33], v[220:223], v[186:189], v[30:33]
	v_mfma_f32_16x16x32_bf16 v[26:29], v[228:231], v[186:189], v[26:29]
	ds_read_b128 v[170:173], v137
	v_mfma_f32_16x16x32_bf16 v[22:25], v[220:223], v[196:199], v[22:25]
	v_mfma_f32_16x16x32_bf16 v[18:21], v[228:231], v[196:199], v[18:21]
	ds_read_b128 v[174:177], v137 offset:1024
	v_mfma_f32_16x16x32_bf16 v[14:17], v[220:223], v[204:207], v[14:17]
	v_mfma_f32_16x16x32_bf16 v[10:13], v[228:231], v[204:207], v[10:13]
	ds_read_b128 v[178:181], v137 offset:2048
	v_mfma_f32_16x16x32_bf16 v[6:9], v[220:223], v[212:215], v[6:9]
	v_mfma_f32_16x16x32_bf16 v[2:5], v[228:231], v[212:215], v[2:5]
	ds_read_b128 v[182:185], v137 offset:3072
	v_mfma_f32_16x16x32_bf16 v[30:33], v[224:227], v[190:193], v[30:33]
	v_mfma_f32_16x16x32_bf16 v[26:29], v[232:235], v[190:193], v[26:29]
	v_mfma_f32_16x16x32_bf16 v[22:25], v[224:227], v[200:203], v[22:25]
	v_mfma_f32_16x16x32_bf16 v[18:21], v[232:235], v[200:203], v[18:21]
	v_mfma_f32_16x16x32_bf16 v[14:17], v[224:227], v[208:211], v[14:17]
	v_mfma_f32_16x16x32_bf16 v[10:13], v[232:235], v[208:211], v[10:13]
	v_mfma_f32_16x16x32_bf16 v[6:9], v[224:227], v[216:219], v[6:9]
	v_mfma_f32_16x16x32_bf16 v[2:5], v[232:235], v[216:219], v[2:5]
	s_barrier
	s_setprio 0
	ds_read_b128 v[186:189], v168 offset:32768
	ds_read_b128 v[190:193], v168 offset:33792
	ds_read_b128 v[196:199], v167 offset:32768
	ds_read_b128 v[200:203], v167 offset:33792
	ds_read_b128 v[204:207], v166 offset:32768
	ds_read_b128 v[208:211], v166 offset:33792
	ds_read_b128 v[212:215], v147 offset:32768
	ds_read_b128 v[216:219], v147 offset:33792
	s_add_u32 s26, s17, 0x8080100
	s_addc_u32 s27, s18, 0
	s_add_u32 m0, s98, 0x4000
	global_load_lds_dwordx4 v132, s[26:27]
	s_add_u32 m0, s98, 0x6000
	global_load_lds_dwordx4 v130, s[26:27]
	s_waitcnt lgkmcnt(8)
	s_setprio 1
	s_barrier
	s_waitcnt lgkmcnt(0)
	v_mfma_f32_16x16x32_bf16 v[126:129], v[170:173], v[186:189], v[126:129]
	v_mfma_f32_16x16x32_bf16 v[122:125], v[178:181], v[186:189], v[122:125]
	v_mfma_f32_16x16x32_bf16 v[118:121], v[170:173], v[196:199], v[118:121]
	v_mfma_f32_16x16x32_bf16 v[114:117], v[178:181], v[196:199], v[114:117]
	v_mfma_f32_16x16x32_bf16 v[110:113], v[170:173], v[204:207], v[110:113]
	v_mfma_f32_16x16x32_bf16 v[106:109], v[178:181], v[204:207], v[106:109]
	v_mfma_f32_16x16x32_bf16 v[102:105], v[170:173], v[212:215], v[102:105]
	v_mfma_f32_16x16x32_bf16 v[98:101], v[178:181], v[212:215], v[98:101]
	v_mfma_f32_16x16x32_bf16 v[126:129], v[174:177], v[190:193], v[126:129]
	v_mfma_f32_16x16x32_bf16 v[122:125], v[182:185], v[190:193], v[122:125]
	v_mfma_f32_16x16x32_bf16 v[118:121], v[174:177], v[200:203], v[118:121]
	v_mfma_f32_16x16x32_bf16 v[114:117], v[182:185], v[200:203], v[114:117]
	v_mfma_f32_16x16x32_bf16 v[110:113], v[174:177], v[208:211], v[110:113]
	v_mfma_f32_16x16x32_bf16 v[106:109], v[182:185], v[208:211], v[106:109]
	v_mfma_f32_16x16x32_bf16 v[102:105], v[174:177], v[216:219], v[102:105]
	v_mfma_f32_16x16x32_bf16 v[98:101], v[182:185], v[216:219], v[98:101]
	s_barrier
	s_setprio 0
	ds_read_b128 v[220:223], v135
	ds_read_b128 v[224:227], v135 offset:1024
	ds_read_b128 v[228:231], v135 offset:2048
	ds_read_b128 v[232:235], v135 offset:3072
	s_add_u32 s26, s19, 0x180
	s_addc_u32 s27, s20, 0
	s_add_u32 m0, s98, 0x18000
	global_load_lds_dwordx4 v132, s[26:27]
	s_add_u32 m0, s98, 0x1a000
	global_load_lds_dwordx4 v130, s[26:27]
	s_setprio 1
	s_barrier
	s_waitcnt lgkmcnt(0)
	v_mfma_f32_16x16x32_bf16 v[94:97], v[220:223], v[186:189], v[94:97]
	v_mfma_f32_16x16x32_bf16 v[90:93], v[228:231], v[186:189], v[90:93]
	v_mfma_f32_16x16x32_bf16 v[86:89], v[220:223], v[196:199], v[86:89]
	v_mfma_f32_16x16x32_bf16 v[82:85], v[228:231], v[196:199], v[82:85]
	v_mfma_f32_16x16x32_bf16 v[78:81], v[220:223], v[204:207], v[78:81]
	v_mfma_f32_16x16x32_bf16 v[74:77], v[228:231], v[204:207], v[74:77]
	v_mfma_f32_16x16x32_bf16 v[70:73], v[220:223], v[212:215], v[70:73]
	v_mfma_f32_16x16x32_bf16 v[66:69], v[228:231], v[212:215], v[66:69]
	v_mfma_f32_16x16x32_bf16 v[94:97], v[224:227], v[190:193], v[94:97]
	v_mfma_f32_16x16x32_bf16 v[90:93], v[232:235], v[190:193], v[90:93]
	v_mfma_f32_16x16x32_bf16 v[86:89], v[224:227], v[200:203], v[86:89]
	v_mfma_f32_16x16x32_bf16 v[82:85], v[232:235], v[200:203], v[82:85]
	v_mfma_f32_16x16x32_bf16 v[78:81], v[224:227], v[208:211], v[78:81]
	v_mfma_f32_16x16x32_bf16 v[74:77], v[232:235], v[208:211], v[74:77]
	v_mfma_f32_16x16x32_bf16 v[70:73], v[224:227], v[216:219], v[70:73]
	v_mfma_f32_16x16x32_bf16 v[66:69], v[232:235], v[216:219], v[66:69]
	s_barrier
	s_setprio 0
	ds_read_b128 v[186:189], v168 offset:49152
	ds_read_b128 v[190:193], v168 offset:50176
	ds_read_b128 v[196:199], v167 offset:49152
	ds_read_b128 v[200:203], v167 offset:50176
	ds_read_b128 v[204:207], v166 offset:49152
	ds_read_b128 v[208:211], v166 offset:50176
	ds_read_b128 v[212:215], v147 offset:49152
	ds_read_b128 v[216:219], v147 offset:50176
	s_add_u32 s26, s17, 0x8000180
	s_addc_u32 s27, s18, 0
	s_add_u32 m0, s98, 0x8000
	global_load_lds_dwordx4 v132, s[26:27]
	s_add_u32 m0, s98, 0xa000
	global_load_lds_dwordx4 v130, s[26:27]
	s_setprio 1
	s_barrier
;   #define LDA(dst,b,h) for(int m=0;m<4;++m)for(int k=0;k<2;++k) \
;     dst[m][k]=*reinterpret_cast<const bf16x8*>((char*)SA(b,h)+lds_byte(wr*64+m*16+fr,k*32+fq*8))
;   #define LDB(dst,b,h) for(int n=0;n<2;++n)for(int k=0;k<2;++k) \
;     dst[n][k]=*reinterpret_cast<const bf16x8*>((char*)SB(b,h)+lds_byte(wc*32+n*16+fr,k*32+fq*8))
;   #define MMA(ai,bj,At,Bt_) do{__builtin_amdgcn_s_setprio(1); \
;     for(int m=0;m<4;++m)for(int n=0;n<2;++n)for(int k=0;k<2;++k) \
;       acc[ai][bj][m][n]=__builtin_amdgcn_mfma_f32_16x16x32_bf16(Bt_[n][k],At[m][k],acc[ai][bj][m][n],0,0,0); \
;     __builtin_amdgcn_s_setprio(0);}while(0)
;   #define WAIT_V(n) asm volatile("s_waitcnt vmcnt(" #n ")":::"memory")
;   #define WAIT_L(n) asm volatile("s_waitcnt lgkmcnt(" #n ")":::"memory")
;   #define BAR __builtin_amdgcn_s_barrier()
;   #define SCHED __builtin_amdgcn_sched_barrier(0)
; template <bool TWO, class MID> ...
;     ...
;     BAR; WAIT_L(0); MMA(1,0,At,B0); BAR; SCHED;
;     STAGE_B(SB(1,1),1,t+3);
;     WAIT_V(6); BAR; MMA(1,1,At,B1); BAR;
;   }
;   { LDB(B0,0,0); LDA(At,0,0); STAGE_A(SA(1,1),1,nt-1);
;     BAR; WAIT_L(0); MMA(0,0,At,B0); BAR;
;     LDB(B1,0,1); BAR; WAIT_L(0); MMA(0,1,At,B1); BAR;
;     LDA(At,0,1); WAIT_V(4); BAR; WAIT_L(0); MMA(1,0,At,B0); MMA(1,1,At,B1); BAR; }
	s_waitcnt lgkmcnt(0)
	v_mfma_f32_16x16x32_bf16 v[62:65], v[170:173], v[186:189], v[62:65]
	v_mfma_f32_16x16x32_bf16 v[58:61], v[178:181], v[186:189], v[58:61]
	v_mfma_f32_16x16x32_bf16 v[54:57], v[170:173], v[196:199], v[54:57]
	v_mfma_f32_16x16x32_bf16 v[50:53], v[178:181], v[196:199], v[50:53]
	v_mfma_f32_16x16x32_bf16 v[46:49], v[170:173], v[204:207], v[46:49]
	v_mfma_f32_16x16x32_bf16 v[42:45], v[178:181], v[204:207], v[42:45]
	v_mfma_f32_16x16x32_bf16 v[38:41], v[170:173], v[212:215], v[38:41]
	v_mfma_f32_16x16x32_bf16 v[34:37], v[178:181], v[212:215], v[34:37]
	v_mfma_f32_16x16x32_bf16 v[62:65], v[174:177], v[190:193], v[62:65]
	v_mfma_f32_16x16x32_bf16 v[58:61], v[182:185], v[190:193], v[58:61]
	v_mfma_f32_16x16x32_bf16 v[54:57], v[174:177], v[200:203], v[54:57]
	v_mfma_f32_16x16x32_bf16 v[50:53], v[182:185], v[200:203], v[50:53]
	v_mfma_f32_16x16x32_bf16 v[46:49], v[174:177], v[208:211], v[46:49]
	v_mfma_f32_16x16x32_bf16 v[42:45], v[182:185], v[208:211], v[42:45]
	v_mfma_f32_16x16x32_bf16 v[38:41], v[174:177], v[216:219], v[38:41]
	v_mfma_f32_16x16x32_bf16 v[34:37], v[182:185], v[216:219], v[34:37]
	s_barrier
	s_setprio 0
	s_add_u32 s18, s19, 0x80180
	s_addc_u32 s19, s20, 0
	s_add_u32 m0, s98, 0x1c000
	global_load_lds_dwordx4 v132, s[18:19]
	s_add_u32 m0, s98, 0x1e000
	global_load_lds_dwordx4 v130, s[18:19]
	s_waitcnt vmcnt(6)
	s_setprio 1
	s_barrier
	v_mfma_f32_16x16x32_bf16 v[30:33], v[220:223], v[186:189], v[30:33]
	v_mfma_f32_16x16x32_bf16 v[26:29], v[228:231], v[186:189], v[26:29]
	v_mfma_f32_16x16x32_bf16 v[22:25], v[220:223], v[196:199], v[22:25]
	v_mfma_f32_16x16x32_bf16 v[18:21], v[228:231], v[196:199], v[18:21]
	v_mfma_f32_16x16x32_bf16 v[14:17], v[220:223], v[204:207], v[14:17]
	v_mfma_f32_16x16x32_bf16 v[10:13], v[228:231], v[204:207], v[10:13]
	v_mfma_f32_16x16x32_bf16 v[6:9], v[220:223], v[212:215], v[6:9]
	v_mfma_f32_16x16x32_bf16 v[2:5], v[228:231], v[212:215], v[2:5]
	v_mfma_f32_16x16x32_bf16 v[30:33], v[224:227], v[190:193], v[30:33]
	v_mfma_f32_16x16x32_bf16 v[26:29], v[232:235], v[190:193], v[26:29]
	v_mfma_f32_16x16x32_bf16 v[22:25], v[224:227], v[200:203], v[22:25]
	v_mfma_f32_16x16x32_bf16 v[18:21], v[232:235], v[200:203], v[18:21]
	v_mfma_f32_16x16x32_bf16 v[14:17], v[224:227], v[208:211], v[14:17]
	v_mfma_f32_16x16x32_bf16 v[10:13], v[232:235], v[208:211], v[10:13]
	v_mfma_f32_16x16x32_bf16 v[6:9], v[224:227], v[216:219], v[6:9]
	v_mfma_f32_16x16x32_bf16 v[2:5], v[232:235], v[216:219], v[2:5]
	s_setprio 0
	s_add_i32 s9, s9, 2
	s_add_u32 s0, s0, 0x100
	s_addc_u32 s1, s1, 0
	s_cmp_lt_u32 s9, 28
	s_barrier
	s_cbranch_scc1 .LBB0_169
	ds_read_b128 v[150:153], v143
	ds_read_b128 v[158:161], v143 offset:1024
	ds_read_b128 v[162:165], v143 offset:2048
	ds_read_b128 v[142:145], v143 offset:3072
	ds_read_b128 v[170:173], v168
	ds_read_b128 v[174:177], v168 offset:1024
	ds_read_b128 v[178:181], v167
	ds_read_b128 v[182:185], v167 offset:1024
	ds_read_b128 v[186:189], v166
	ds_read_b128 v[190:193], v166 offset:1024
	ds_read_b128 v[196:199], v147
	ds_read_b128 v[200:203], v147 offset:1024
	s_add_u32 s0, s11, 0x80f80
	s_addc_u32 s1, s16, 0
	v_lshl_add_u64 v[132:133], s[0:1], 0, v[132:133]
	v_readfirstlane_b32 s9, v148
	s_mov_b32 m0, s9
	global_load_lds_dwordx4 v[132:133], off
	v_lshl_add_u64 v[130:131], s[0:1], 0, v[130:131]
	v_readfirstlane_b32 s0, v156
	s_mov_b32 m0, s0
	global_load_lds_dwordx4 v[130:131], off
	s_setprio 1
	s_barrier
	s_waitcnt lgkmcnt(0)
	v_mfma_f32_16x16x32_bf16 v[126:129], v[150:153], v[170:173], v[126:129]
	v_mfma_f32_16x16x32_bf16 v[122:125], v[162:165], v[170:173], v[122:125]
	v_mfma_f32_16x16x32_bf16 v[114:117], v[162:165], v[178:181], v[114:117]
	v_mfma_f32_16x16x32_bf16 v[106:109], v[162:165], v[186:189], v[106:109]
	v_mfma_f32_16x16x32_bf16 v[98:101], v[162:165], v[196:199], v[98:101]
	v_mfma_f32_16x16x32_bf16 v[126:129], v[158:161], v[174:177], v[126:129]
	v_mfma_f32_16x16x32_bf16 v[122:125], v[142:145], v[174:177], v[122:125]
	v_mfma_f32_16x16x32_bf16 v[118:121], v[150:153], v[178:181], v[118:121]
	v_mfma_f32_16x16x32_bf16 v[114:117], v[142:145], v[182:185], v[114:117]
	v_mfma_f32_16x16x32_bf16 v[110:113], v[150:153], v[186:189], v[110:113]
	v_mfma_f32_16x16x32_bf16 v[106:109], v[142:145], v[190:193], v[106:109]
	v_mfma_f32_16x16x32_bf16 v[102:105], v[150:153], v[196:199], v[102:105]
	v_mfma_f32_16x16x32_bf16 v[130:133], v[142:145], v[200:203], v[98:101]
	v_mfma_f32_16x16x32_bf16 v[118:121], v[158:161], v[182:185], v[118:121]
	v_mfma_f32_16x16x32_bf16 v[110:113], v[158:161], v[190:193], v[110:113]
	v_mfma_f32_16x16x32_bf16 v[102:105], v[158:161], v[200:203], v[102:105]
	s_barrier
	s_setprio 0
	ds_read_b128 v[98:101], v141
	ds_read_b128 v[154:157], v141 offset:1024
	ds_read_b128 v[204:207], v141 offset:2048
	ds_read_b128 v[138:141], v141 offset:3072
	s_setprio 1
	s_barrier
	s_waitcnt lgkmcnt(0)
	v_mfma_f32_16x16x32_bf16 v[86:89], v[98:101], v[178:181], v[86:89]
	v_mfma_f32_16x16x32_bf16 v[82:85], v[204:207], v[178:181], v[82:85]
	v_mfma_f32_16x16x32_bf16 v[70:73], v[98:101], v[196:199], v[70:73]
	v_mfma_f32_16x16x32_bf16 v[66:69], v[204:207], v[196:199], v[66:69]
	v_mfma_f32_16x16x32_bf16 v[94:97], v[98:101], v[170:173], v[94:97]
	v_mfma_f32_16x16x32_bf16 v[90:93], v[204:207], v[170:173], v[90:93]
	v_mfma_f32_16x16x32_bf16 v[86:89], v[154:157], v[182:185], v[86:89]
	v_mfma_f32_16x16x32_bf16 v[82:85], v[138:141], v[182:185], v[82:85]
	v_mfma_f32_16x16x32_bf16 v[78:81], v[98:101], v[186:189], v[78:81]
	v_mfma_f32_16x16x32_bf16 v[74:77], v[204:207], v[186:189], v[74:77]
	v_mfma_f32_16x16x32_bf16 v[70:73], v[154:157], v[200:203], v[70:73]
	v_mfma_f32_16x16x32_bf16 v[66:69], v[138:141], v[200:203], v[66:69]
	v_mfma_f32_16x16x32_bf16 v[94:97], v[154:157], v[174:177], v[94:97]
	v_mfma_f32_16x16x32_bf16 v[170:173], v[138:141], v[174:177], v[90:93]
	v_mfma_f32_16x16x32_bf16 v[174:177], v[154:157], v[190:193], v[78:81]
	v_mfma_f32_16x16x32_bf16 v[178:181], v[138:141], v[190:193], v[74:77]
	s_barrier
;   #define LDA(dst,b,h) for(int m=0;m<4;++m)for(int k=0;k<2;++k) \
;     dst[m][k]=*reinterpret_cast<const bf16x8*>((char*)SA(b,h)+lds_byte(wr*64+m*16+fr,k*32+fq*8))
;   #define LDB(dst,b,h) for(int n=0;n<2;++n)for(int k=0;k<2;++k) \
;     dst[n][k]=*reinterpret_cast<const bf16x8*>((char*)SB(b,h)+lds_byte(wc*32+n*16+fr,k*32+fq*8))
;   #define MMA(ai,bj,At,Bt_) do{__builtin_amdgcn_s_setprio(1); \
;     for(int m=0;m<4;++m)for(int n=0;n<2;++n)for(int k=0;k<2;++k) \
;       acc[ai][bj][m][n]=__builtin_amdgcn_mfma_f32_16x16x32_bf16(Bt_[n][k],At[m][k],acc[ai][bj][m][n],0,0,0); \
;     __builtin_amdgcn_s_setprio(0);}while(0)
;   #define WAIT_V(n) asm volatile("s_waitcnt vmcnt(" #n ")":::"memory")
;   #define WAIT_L(n) asm volatile("s_waitcnt lgkmcnt(" #n ")":::"memory")
;   #define BAR __builtin_amdgcn_s_barrier()
; template <bool TWO, class MID> ...
;     ...
;     LDA(At,0,1); WAIT_V(4); BAR; WAIT_L(0); MMA(1,0,At,B0); MMA(1,1,At,B1); BAR; }
;   { LDB(B0,1,0); LDA(At,1,0); WAIT_V(2); BAR; WAIT_L(0); MMA(0,0,At,B0); BAR;
	s_setprio 0
	s_nop 0
	ds_read_b128 v[74:77], v168 offset:16384
	ds_read_b128 v[78:81], v168 offset:17408
	ds_read_b128 v[90:93], v167 offset:16384
	ds_read_b128 v[182:185], v167 offset:17408
	ds_read_b128 v[186:189], v166 offset:16384
	ds_read_b128 v[190:193], v166 offset:17408
	ds_read_b128 v[196:199], v147 offset:16384
	ds_read_b128 v[200:203], v147 offset:17408
	s_waitcnt vmcnt(4)
	s_setprio 1
	s_barrier
	s_waitcnt lgkmcnt(0)
	v_mfma_f32_16x16x32_bf16 v[62:65], v[150:153], v[74:77], v[62:65]
	v_mfma_f32_16x16x32_bf16 v[58:61], v[162:165], v[74:77], v[58:61]
	v_mfma_f32_16x16x32_bf16 v[54:57], v[150:153], v[90:93], v[54:57]
	v_mfma_f32_16x16x32_bf16 v[50:53], v[162:165], v[90:93], v[50:53]
	v_mfma_f32_16x16x32_bf16 v[38:41], v[150:153], v[196:199], v[38:41]
	v_mfma_f32_16x16x32_bf16 v[34:37], v[162:165], v[196:199], v[34:37]
	v_mfma_f32_16x16x32_bf16 v[62:65], v[158:161], v[78:81], v[62:65]
	v_mfma_f32_16x16x32_bf16 v[58:61], v[142:145], v[78:81], v[58:61]
	v_mfma_f32_16x16x32_bf16 v[54:57], v[158:161], v[182:185], v[54:57]
	v_mfma_f32_16x16x32_bf16 v[50:53], v[142:145], v[182:185], v[50:53]
	v_mfma_f32_16x16x32_bf16 v[46:49], v[150:153], v[186:189], v[46:49]
	v_mfma_f32_16x16x32_bf16 v[42:45], v[162:165], v[186:189], v[42:45]
	v_mfma_f32_16x16x32_bf16 v[38:41], v[158:161], v[200:203], v[38:41]
	v_mfma_f32_16x16x32_bf16 v[34:37], v[142:145], v[200:203], v[34:37]
	v_mfma_f32_16x16x32_bf16 v[208:211], v[158:161], v[190:193], v[46:49]
	v_mfma_f32_16x16x32_bf16 v[212:215], v[142:145], v[190:193], v[42:45]
	s_setprio 0
	s_setprio 1
	v_mfma_f32_16x16x32_bf16 v[22:25], v[98:101], v[90:93], v[22:25]
	v_mfma_f32_16x16x32_bf16 v[18:21], v[204:207], v[90:93], v[18:21]
	v_mfma_f32_16x16x32_bf16 v[6:9], v[98:101], v[196:199], v[6:9]
	v_mfma_f32_16x16x32_bf16 v[2:5], v[204:207], v[196:199], v[2:5]
	v_mfma_f32_16x16x32_bf16 v[30:33], v[98:101], v[74:77], v[30:33]
	v_mfma_f32_16x16x32_bf16 v[26:29], v[204:207], v[74:77], v[26:29]
	v_mfma_f32_16x16x32_bf16 v[22:25], v[154:157], v[182:185], v[22:25]
	v_mfma_f32_16x16x32_bf16 v[18:21], v[138:141], v[182:185], v[18:21]
	v_mfma_f32_16x16x32_bf16 v[14:17], v[98:101], v[186:189], v[14:17]
	v_mfma_f32_16x16x32_bf16 v[10:13], v[204:207], v[186:189], v[10:13]
	v_mfma_f32_16x16x32_bf16 v[6:9], v[154:157], v[200:203], v[6:9]
	v_mfma_f32_16x16x32_bf16 v[2:5], v[138:141], v[200:203], v[2:5]
	v_mfma_f32_16x16x32_bf16 v[148:151], v[154:157], v[78:81], v[30:33]
	v_mfma_f32_16x16x32_bf16 v[158:161], v[138:141], v[78:81], v[26:29]
	v_mfma_f32_16x16x32_bf16 v[162:165], v[154:157], v[190:193], v[14:17]
	v_mfma_f32_16x16x32_bf16 v[182:185], v[138:141], v[190:193], v[10:13]
	s_barrier
	s_setprio 0
	s_nop 0
	ds_read_b128 v[10:13], v137
	ds_read_b128 v[14:17], v137 offset:1024
	ds_read_b128 v[152:155], v137 offset:2048
	ds_read_b128 v[186:189], v137 offset:3072
	ds_read_b128 v[26:29], v168 offset:32768
	ds_read_b128 v[30:33], v168 offset:33792
	ds_read_b128 v[42:45], v167 offset:32768
	ds_read_b128 v[46:49], v167 offset:33792
	ds_read_b128 v[190:193], v166 offset:32768
	ds_read_b128 v[196:199], v166 offset:33792
	ds_read_b128 v[200:203], v147 offset:32768
	ds_read_b128 v[204:207], v147 offset:33792
	s_waitcnt vmcnt(2)
	s_setprio 1
	s_barrier
	s_waitcnt lgkmcnt(0)
	v_mfma_f32_16x16x32_bf16 v[74:77], v[10:13], v[26:29], v[126:129]
	v_mfma_f32_16x16x32_bf16 v[142:145], v[14:17], v[30:33], v[74:77]
	v_mfma_f32_16x16x32_bf16 v[74:77], v[152:155], v[26:29], v[122:125]
	v_mfma_f32_16x16x32_bf16 v[138:141], v[186:189], v[30:33], v[74:77]
	v_mfma_f32_16x16x32_bf16 v[74:77], v[10:13], v[42:45], v[118:121]
	v_mfma_f32_16x16x32_bf16 v[126:129], v[14:17], v[46:49], v[74:77]
	v_mfma_f32_16x16x32_bf16 v[74:77], v[152:155], v[42:45], v[114:117]
	v_mfma_f32_16x16x32_bf16 v[122:125], v[186:189], v[46:49], v[74:77]
	v_mfma_f32_16x16x32_bf16 v[74:77], v[10:13], v[190:193], v[110:113]
	v_mfma_f32_16x16x32_bf16 v[98:101], v[14:17], v[196:199], v[74:77]
	v_mfma_f32_16x16x32_bf16 v[74:77], v[152:155], v[190:193], v[106:109]
	v_mfma_f32_16x16x32_bf16 v[90:93], v[186:189], v[196:199], v[74:77]
	v_mfma_f32_16x16x32_bf16 v[74:77], v[10:13], v[200:203], v[102:105]
	v_mfma_f32_16x16x32_bf16 v[78:81], v[14:17], v[204:207], v[74:77]
	v_mfma_f32_16x16x32_bf16 v[74:77], v[152:155], v[200:203], v[130:133]
	v_mfma_f32_16x16x32_bf16 v[74:77], v[186:189], v[204:207], v[74:77]
	s_barrier
;   #define LDA(dst,b,h) for(int m=0;m<4;++m)for(int k=0;k<2;++k) \
;     dst[m][k]=*reinterpret_cast<const bf16x8*>((char*)SA(b,h)+lds_byte(wr*64+m*16+fr,k*32+fq*8))
;   #define LDB(dst,b,h) for(int n=0;n<2;++n)for(int k=0;k<2;++k) \
;     dst[n][k]=*reinterpret_cast<const bf16x8*>((char*)SB(b,h)+lds_byte(wc*32+n*16+fr,k*32+fq*8))
;   #define MMA(ai,bj,At,Bt_) do{__builtin_amdgcn_s_setprio(1); \
;     for(int m=0;m<4;++m)for(int n=0;n<2;++n)for(int k=0;k<2;++k) \
;       acc[ai][bj][m][n]=__builtin_amdgcn_mfma_f32_16x16x32_bf16(Bt_[n][k],At[m][k],acc[ai][bj][m][n],0,0,0); \
;     __builtin_amdgcn_s_setprio(0);}while(0)
;   #define WAIT_V(n) asm volatile("s_waitcnt vmcnt(" #n ")":::"memory")
;   #define WAIT_L(n) asm volatile("s_waitcnt lgkmcnt(" #n ")":::"memory")
;   #define BAR __builtin_amdgcn_s_barrier()
; template <bool TWO, class MID> ...
;     ...
;     LDB(B1,1,1); WAIT_V(0); BAR; WAIT_L(0); MMA(0,1,At,B1); BAR;
;     LDA(At,1,1); BAR; WAIT_L(0); MMA(1,0,At,B0); MMA(1,1,At,B1); BAR; }
;   if(wr==0)BAR;
	s_setprio 0
	ds_read_b128 v[102:105], v135
	ds_read_b128 v[110:113], v135 offset:1024
	ds_read_b128 v[118:121], v135 offset:2048
	ds_read_b128 v[216:219], v135 offset:3072
	s_waitcnt vmcnt(0)
	s_setprio 1
	s_barrier
	s_waitcnt lgkmcnt(0)
	v_mfma_f32_16x16x32_bf16 v[94:97], v[102:105], v[26:29], v[94:97]
	v_mfma_f32_16x16x32_bf16 v[26:29], v[118:121], v[26:29], v[170:173]
	v_mfma_f32_16x16x32_bf16 v[130:133], v[216:219], v[30:33], v[26:29]
	v_mfma_f32_16x16x32_bf16 v[26:29], v[102:105], v[42:45], v[86:89]
	v_mfma_f32_16x16x32_bf16 v[114:117], v[110:113], v[46:49], v[26:29]
	v_mfma_f32_16x16x32_bf16 v[26:29], v[118:121], v[42:45], v[82:85]
	v_mfma_f32_16x16x32_bf16 v[106:109], v[216:219], v[46:49], v[26:29]
	v_mfma_f32_16x16x32_bf16 v[26:29], v[102:105], v[190:193], v[174:177]
	v_mfma_f32_16x16x32_bf16 v[86:89], v[110:113], v[196:199], v[26:29]
	v_mfma_f32_16x16x32_bf16 v[26:29], v[118:121], v[190:193], v[178:181]
	v_mfma_f32_16x16x32_bf16 v[82:85], v[216:219], v[196:199], v[26:29]
	v_mfma_f32_16x16x32_bf16 v[26:29], v[102:105], v[200:203], v[70:73]
	v_mfma_f32_16x16x32_bf16 v[70:73], v[110:113], v[204:207], v[26:29]
	v_mfma_f32_16x16x32_bf16 v[26:29], v[118:121], v[200:203], v[66:69]
	v_mfma_f32_16x16x32_bf16 v[134:137], v[110:113], v[30:33], v[94:97]
	v_mfma_f32_16x16x32_bf16 v[66:69], v[216:219], v[204:207], v[26:29]
	s_barrier
	s_setprio 0
	ds_read_b128 v[94:97], v168 offset:49152
	ds_read_b128 v[168:171], v168 offset:50176
	ds_read_b128 v[172:175], v167 offset:49152
	ds_read_b128 v[176:179], v167 offset:50176
	ds_read_b128 v[190:193], v166 offset:49152
	ds_read_b128 v[196:199], v166 offset:50176
	ds_read_b128 v[200:203], v147 offset:49152
	ds_read_b128 v[204:207], v147 offset:50176
	s_setprio 1
	s_barrier
	s_waitcnt lgkmcnt(0)
	v_mfma_f32_16x16x32_bf16 v[26:29], v[10:13], v[94:97], v[62:65]
	v_mfma_f32_16x16x32_bf16 v[62:65], v[14:17], v[168:171], v[26:29]
	v_mfma_f32_16x16x32_bf16 v[26:29], v[152:155], v[94:97], v[58:61]
	v_mfma_f32_16x16x32_bf16 v[58:61], v[186:189], v[168:171], v[26:29]
	v_mfma_f32_16x16x32_bf16 v[26:29], v[10:13], v[172:175], v[54:57]
	v_mfma_f32_16x16x32_bf16 v[46:49], v[14:17], v[176:179], v[26:29]
	v_mfma_f32_16x16x32_bf16 v[26:29], v[152:155], v[172:175], v[50:53]
	v_mfma_f32_16x16x32_bf16 v[42:45], v[186:189], v[176:179], v[26:29]
	v_mfma_f32_16x16x32_bf16 v[26:29], v[10:13], v[190:193], v[208:211]
	v_mfma_f32_16x16x32_bf16 v[10:13], v[10:13], v[200:203], v[38:41]
	v_mfma_f32_16x16x32_bf16 v[30:33], v[14:17], v[196:199], v[26:29]
	v_mfma_f32_16x16x32_bf16 v[26:29], v[152:155], v[190:193], v[212:215]
	v_mfma_f32_16x16x32_bf16 v[14:17], v[14:17], v[204:207], v[10:13]
	v_mfma_f32_16x16x32_bf16 v[10:13], v[152:155], v[200:203], v[34:37]
	v_mfma_f32_16x16x32_bf16 v[26:29], v[186:189], v[196:199], v[26:29]
	v_mfma_f32_16x16x32_bf16 v[10:13], v[186:189], v[204:207], v[10:13]
	s_setprio 0
	s_setprio 1
	v_mfma_f32_16x16x32_bf16 v[34:37], v[102:105], v[94:97], v[148:151]
	v_mfma_f32_16x16x32_bf16 v[54:57], v[110:113], v[168:171], v[34:37]
	v_mfma_f32_16x16x32_bf16 v[34:37], v[118:121], v[94:97], v[158:161]
	v_mfma_f32_16x16x32_bf16 v[18:21], v[118:121], v[172:175], v[18:21]
	v_mfma_f32_16x16x32_bf16 v[50:53], v[216:219], v[168:171], v[34:37]
	v_mfma_f32_16x16x32_bf16 v[22:25], v[102:105], v[172:175], v[22:25]
	v_mfma_f32_16x16x32_bf16 v[34:37], v[216:219], v[176:179], v[18:21]
	v_mfma_f32_16x16x32_bf16 v[18:21], v[102:105], v[190:193], v[162:165]
	v_mfma_f32_16x16x32_bf16 v[38:41], v[110:113], v[176:179], v[22:25]
	v_mfma_f32_16x16x32_bf16 v[22:25], v[110:113], v[196:199], v[18:21]
	v_mfma_f32_16x16x32_bf16 v[18:21], v[118:121], v[190:193], v[182:185]
	v_mfma_f32_16x16x32_bf16 v[6:9], v[102:105], v[200:203], v[6:9]
	v_mfma_f32_16x16x32_bf16 v[2:5], v[118:121], v[200:203], v[2:5]
	v_mfma_f32_16x16x32_bf16 v[18:21], v[216:219], v[196:199], v[18:21]
	v_mfma_f32_16x16x32_bf16 v[6:9], v[110:113], v[204:207], v[6:9]
	v_mfma_f32_16x16x32_bf16 v[2:5], v[216:219], v[204:207], v[2:5]
	s_setprio 0
	v_cmp_gt_u32_e32 vcc, s30, v1
	s_barrier
	s_and_saveexec_b64 s[0:1], vcc
	s_cbranch_execz .LBB0_172
	s_barrier

;   #define LDA(dst,b,h) for(int m=0;m<4;++m)for(int k=0;k<2;++k) \
;     dst[m][k]=*reinterpret_cast<const bf16x8*>((char*)SA(b,h)+lds_byte(wr*64+m*16+fr,k*32+fq*8))
;   #define LDB(dst,b,h) for(int n=0;n<2;++n)for(int k=0;k<2;++k) \
;     dst[n][k]=*reinterpret_cast<const bf16x8*>((char*)SB(b,h)+lds_byte(wc*32+n*16+fr,k*32+fq*8))
;   #define MMA(ai,bj,At,Bt_) do{__builtin_amdgcn_s_setprio(1); \
;     for(int m=0;m<4;++m)for(int n=0;n<2;++n)for(int k=0;k<2;++k) \
;       acc[ai][bj][m][n]=__builtin_amdgcn_mfma_f32_16x16x32_bf16(Bt_[n][k],At[m][k],acc[ai][bj][m][n],0,0,0); \
;     __builtin_amdgcn_s_setprio(0);}while(0)
;   #define WAIT_V(n) asm volatile("s_waitcnt vmcnt(" #n ")":::"memory")
;   #define WAIT_L(n) asm volatile("s_waitcnt lgkmcnt(" #n ")":::"memory")
;   #define BAR __builtin_amdgcn_s_barrier()
;   #define SCHED __builtin_amdgcn_sched_barrier(0)
; template <bool TWO, class MID> ...
;     ...
;   for(int t=0;t<nt-2;t+=2){
;     if (TWO && t == nt1) mid();
;     LDB(B0,0,0); SCHED; LDA(At,0,0); STAGE_A(SA(1,1),1,t+1);
;     WAIT_L(8); BAR; WAIT_L(0); MMA(0,0,At,B0); BAR; SCHED;
;     LDB(B1,0,1); STAGE_B(SB(0,0),0,t+2);
;     BAR; WAIT_L(0); MMA(0,1,At,B1); BAR;
;     LDA(At,0,1); STAGE_A(SA(0,0),0,t+2);
;     BAR; WAIT_L(0); MMA(1,0,At,B0); BAR; SCHED;
;     STAGE_B(SB(0,1),1,t+2);
;     WAIT_V(6); BAR; MMA(1,1,At,B1); BAR;
.LBB0_489:
	ds_read_b128 v[166:169], v149
	ds_read_b128 v[170:173], v149 offset:1024
	ds_read_b128 v[174:177], v149 offset:2048
	ds_read_b128 v[178:181], v149 offset:3072
	ds_read_b128 v[182:185], v141
	ds_read_b128 v[186:189], v141 offset:1024
	ds_read_b128 v[190:193], v139
	ds_read_b128 v[196:199], v139 offset:1024
	ds_read_b128 v[200:203], v137
	ds_read_b128 v[204:207], v137 offset:1024
	ds_read_b128 v[208:211], v135
	ds_read_b128 v[212:215], v135 offset:1024
	s_add_u32 s19, s4, s10
	s_addc_u32 s24, s5, s11
	s_add_u32 s26, s19, 0x36080080
	s_addc_u32 s27, s24, 0
	s_add_u32 m0, s98, 0xc000
	global_load_lds_dwordx4 v132, s[26:27]
	s_add_u32 m0, s98, 0xe000
	global_load_lds_dwordx4 v130, s[26:27]
	s_waitcnt lgkmcnt(8)
	s_setprio 1
	s_barrier
	s_waitcnt lgkmcnt(0)
	v_mfma_f32_16x16x32_bf16 v[126:129], v[166:169], v[182:185], v[126:129]
	v_mfma_f32_16x16x32_bf16 v[122:125], v[174:177], v[182:185], v[122:125]
	v_mfma_f32_16x16x32_bf16 v[118:121], v[166:169], v[190:193], v[118:121]
	v_mfma_f32_16x16x32_bf16 v[114:117], v[174:177], v[190:193], v[114:117]
	v_mfma_f32_16x16x32_bf16 v[110:113], v[166:169], v[200:203], v[110:113]
	v_mfma_f32_16x16x32_bf16 v[106:109], v[174:177], v[200:203], v[106:109]
	v_mfma_f32_16x16x32_bf16 v[102:105], v[166:169], v[208:211], v[102:105]
	v_mfma_f32_16x16x32_bf16 v[98:101], v[174:177], v[208:211], v[98:101]
	v_mfma_f32_16x16x32_bf16 v[126:129], v[170:173], v[186:189], v[126:129]
	v_mfma_f32_16x16x32_bf16 v[122:125], v[178:181], v[186:189], v[122:125]
	v_mfma_f32_16x16x32_bf16 v[118:121], v[170:173], v[196:199], v[118:121]
	v_mfma_f32_16x16x32_bf16 v[114:117], v[178:181], v[196:199], v[114:117]
	v_mfma_f32_16x16x32_bf16 v[110:113], v[170:173], v[204:207], v[110:113]
	v_mfma_f32_16x16x32_bf16 v[106:109], v[178:181], v[204:207], v[106:109]
	v_mfma_f32_16x16x32_bf16 v[102:105], v[170:173], v[212:215], v[102:105]
	v_mfma_f32_16x16x32_bf16 v[98:101], v[178:181], v[212:215], v[98:101]
	s_barrier
	s_setprio 0
	s_add_u32 s25, s4, s16
	ds_read_b128 v[216:219], v147
	ds_read_b128 v[220:223], v147 offset:1024
	ds_read_b128 v[224:227], v147 offset:2048
	ds_read_b128 v[228:231], v147 offset:3072
	s_addc_u32 s26, s5, s17
	s_add_u32 s28, s25, 0x3400100
	s_addc_u32 s29, s26, 0
	s_add_u32 m0, s98, 0x10000
	global_load_lds_dwordx4 v132, s[28:29]
	s_add_u32 m0, s98, 0x12000
	global_load_lds_dwordx4 v130, s[28:29]
	s_setprio 1
	s_barrier
	s_waitcnt lgkmcnt(0)
	v_mfma_f32_16x16x32_bf16 v[94:97], v[216:219], v[182:185], v[94:97]
	v_mfma_f32_16x16x32_bf16 v[90:93], v[224:227], v[182:185], v[90:93]
	v_mfma_f32_16x16x32_bf16 v[86:89], v[216:219], v[190:193], v[86:89]
	v_mfma_f32_16x16x32_bf16 v[82:85], v[224:227], v[190:193], v[82:85]
	v_mfma_f32_16x16x32_bf16 v[78:81], v[216:219], v[200:203], v[78:81]
	v_mfma_f32_16x16x32_bf16 v[74:77], v[224:227], v[200:203], v[74:77]
	v_mfma_f32_16x16x32_bf16 v[70:73], v[216:219], v[208:211], v[70:73]
	v_mfma_f32_16x16x32_bf16 v[66:69], v[224:227], v[208:211], v[66:69]
	v_mfma_f32_16x16x32_bf16 v[94:97], v[220:223], v[186:189], v[94:97]
	v_mfma_f32_16x16x32_bf16 v[90:93], v[228:231], v[186:189], v[90:93]
	v_mfma_f32_16x16x32_bf16 v[86:89], v[220:223], v[196:199], v[86:89]
	v_mfma_f32_16x16x32_bf16 v[82:85], v[228:231], v[196:199], v[82:85]
	v_mfma_f32_16x16x32_bf16 v[78:81], v[220:223], v[204:207], v[78:81]
	v_mfma_f32_16x16x32_bf16 v[74:77], v[228:231], v[204:207], v[74:77]
	v_mfma_f32_16x16x32_bf16 v[70:73], v[220:223], v[212:215], v[70:73]
	v_mfma_f32_16x16x32_bf16 v[66:69], v[228:231], v[212:215], v[66:69]
	s_barrier
	s_setprio 0
	ds_read_b128 v[182:185], v141 offset:16384
	ds_read_b128 v[186:189], v141 offset:17408
	ds_read_b128 v[190:193], v139 offset:16384
	ds_read_b128 v[196:199], v139 offset:17408
	ds_read_b128 v[200:203], v137 offset:16384
	ds_read_b128 v[204:207], v137 offset:17408
	ds_read_b128 v[208:211], v135 offset:16384
	ds_read_b128 v[212:215], v135 offset:17408
	s_add_u32 s28, s19, 0x36000100
	s_addc_u32 s29, s24, 0
	s_add_u32 m0, s98, 0x0
	global_load_lds_dwordx4 v132, s[28:29]
	s_add_u32 m0, s98, 0x2000
	global_load_lds_dwordx4 v130, s[28:29]
	s_setprio 1
	s_barrier
	s_waitcnt lgkmcnt(0)
	v_mfma_f32_16x16x32_bf16 v[62:65], v[166:169], v[182:185], v[62:65]
	v_mfma_f32_16x16x32_bf16 v[58:61], v[174:177], v[182:185], v[58:61]
	v_mfma_f32_16x16x32_bf16 v[54:57], v[166:169], v[190:193], v[54:57]
	v_mfma_f32_16x16x32_bf16 v[50:53], v[174:177], v[190:193], v[50:53]
	v_mfma_f32_16x16x32_bf16 v[46:49], v[166:169], v[200:203], v[46:49]
	v_mfma_f32_16x16x32_bf16 v[42:45], v[174:177], v[200:203], v[42:45]
	v_mfma_f32_16x16x32_bf16 v[38:41], v[166:169], v[208:211], v[38:41]
	v_mfma_f32_16x16x32_bf16 v[34:37], v[174:177], v[208:211], v[34:37]
	v_mfma_f32_16x16x32_bf16 v[62:65], v[170:173], v[186:189], v[62:65]
	v_mfma_f32_16x16x32_bf16 v[58:61], v[178:181], v[186:189], v[58:61]
	v_mfma_f32_16x16x32_bf16 v[54:57], v[170:173], v[196:199], v[54:57]
	v_mfma_f32_16x16x32_bf16 v[50:53], v[178:181], v[196:199], v[50:53]
	v_mfma_f32_16x16x32_bf16 v[46:49], v[170:173], v[204:207], v[46:49]
	v_mfma_f32_16x16x32_bf16 v[42:45], v[178:181], v[204:207], v[42:45]
	v_mfma_f32_16x16x32_bf16 v[38:41], v[170:173], v[212:215], v[38:41]
	v_mfma_f32_16x16x32_bf16 v[34:37], v[178:181], v[212:215], v[34:37]
	s_barrier
	s_setprio 0
	s_add_u32 s28, s25, 0x3480100
	s_addc_u32 s29, s26, 0
	s_add_u32 m0, s98, 0x14000
	global_load_lds_dwordx4 v132, s[28:29]
	s_add_u32 m0, s98, 0x16000
	global_load_lds_dwordx4 v130, s[28:29]
	s_waitcnt vmcnt(6)
	s_setprio 1
	s_barrier
;   #define LDA(dst,b,h) for(int m=0;m<4;++m)for(int k=0;k<2;++k) \
;     dst[m][k]=*reinterpret_cast<const bf16x8*>((char*)SA(b,h)+lds_byte(wr*64+m*16+fr,k*32+fq*8))
;   #define LDB(dst,b,h) for(int n=0;n<2;++n)for(int k=0;k<2;++k) \
;     dst[n][k]=*reinterpret_cast<const bf16x8*>((char*)SB(b,h)+lds_byte(wc*32+n*16+fr,k*32+fq*8))
;   #define MMA(ai,bj,At,Bt_) do{__builtin_amdgcn_s_setprio(1); \
;     for(int m=0;m<4;++m)for(int n=0;n<2;++n)for(int k=0;k<2;++k) \
;       acc[ai][bj][m][n]=__builtin_amdgcn_mfma_f32_16x16x32_bf16(Bt_[n][k],At[m][k],acc[ai][bj][m][n],0,0,0); \
;     __builtin_amdgcn_s_setprio(0);}while(0)
;   #define WAIT_V(n) asm volatile("s_waitcnt vmcnt(" #n ")":::"memory")
;   #define WAIT_L(n) asm volatile("s_waitcnt lgkmcnt(" #n ")":::"memory")
;   #define BAR __builtin_amdgcn_s_barrier()
;   #define SCHED __builtin_amdgcn_sched_barrier(0)
; template <bool TWO, class MID> ...
;     ...
;     WAIT_V(6); BAR; MMA(1,1,At,B1); BAR;
;     LDB(B0,1,0); SCHED; LDA(At,1,0); STAGE_A(SA(0,1),1,t+2);
;     WAIT_L(8); BAR; WAIT_L(0); MMA(0,0,At,B0); BAR; SCHED;
;     LDB(B1,1,1); STAGE_B(SB(1,0),0,t+3);
;     BAR; WAIT_L(0); MMA(0,1,At,B1); BAR;
;     LDA(At,1,1); STAGE_A(SA(1,0),0,t+3);
;     BAR; WAIT_L(0); MMA(1,0,At,B0); BAR; SCHED;
	v_mfma_f32_16x16x32_bf16 v[30:33], v[216:219], v[182:185], v[30:33]
	v_mfma_f32_16x16x32_bf16 v[26:29], v[224:227], v[182:185], v[26:29]
	ds_read_b128 v[166:169], v145
	v_mfma_f32_16x16x32_bf16 v[22:25], v[216:219], v[190:193], v[22:25]
	v_mfma_f32_16x16x32_bf16 v[18:21], v[224:227], v[190:193], v[18:21]
	ds_read_b128 v[170:173], v145 offset:1024
	v_mfma_f32_16x16x32_bf16 v[14:17], v[216:219], v[200:203], v[14:17]
	v_mfma_f32_16x16x32_bf16 v[10:13], v[224:227], v[200:203], v[10:13]
	ds_read_b128 v[174:177], v145 offset:2048
	v_mfma_f32_16x16x32_bf16 v[6:9], v[216:219], v[208:211], v[6:9]
	v_mfma_f32_16x16x32_bf16 v[2:5], v[224:227], v[208:211], v[2:5]
	ds_read_b128 v[178:181], v145 offset:3072
	v_mfma_f32_16x16x32_bf16 v[30:33], v[220:223], v[186:189], v[30:33]
	v_mfma_f32_16x16x32_bf16 v[26:29], v[228:231], v[186:189], v[26:29]
	v_mfma_f32_16x16x32_bf16 v[22:25], v[220:223], v[196:199], v[22:25]
	v_mfma_f32_16x16x32_bf16 v[18:21], v[228:231], v[196:199], v[18:21]
	v_mfma_f32_16x16x32_bf16 v[14:17], v[220:223], v[204:207], v[14:17]
	v_mfma_f32_16x16x32_bf16 v[10:13], v[228:231], v[204:207], v[10:13]
	v_mfma_f32_16x16x32_bf16 v[6:9], v[220:223], v[212:215], v[6:9]
	v_mfma_f32_16x16x32_bf16 v[2:5], v[228:231], v[212:215], v[2:5]
	s_barrier
	s_setprio 0
	ds_read_b128 v[182:185], v141 offset:32768
	ds_read_b128 v[186:189], v141 offset:33792
	ds_read_b128 v[190:193], v139 offset:32768
	ds_read_b128 v[196:199], v139 offset:33792
	ds_read_b128 v[200:203], v137 offset:32768
	ds_read_b128 v[204:207], v137 offset:33792
	ds_read_b128 v[208:211], v135 offset:32768
	ds_read_b128 v[212:215], v135 offset:33792
	s_add_u32 s28, s19, 0x36080100
	s_addc_u32 s29, s24, 0
	s_add_u32 m0, s98, 0x4000
	global_load_lds_dwordx4 v132, s[28:29]
	s_add_u32 m0, s98, 0x6000
	global_load_lds_dwordx4 v130, s[28:29]
	s_waitcnt lgkmcnt(8)
	s_setprio 1
	s_barrier
	s_waitcnt lgkmcnt(0)
	v_mfma_f32_16x16x32_bf16 v[126:129], v[166:169], v[182:185], v[126:129]
	v_mfma_f32_16x16x32_bf16 v[122:125], v[174:177], v[182:185], v[122:125]
	v_mfma_f32_16x16x32_bf16 v[118:121], v[166:169], v[190:193], v[118:121]
	v_mfma_f32_16x16x32_bf16 v[114:117], v[174:177], v[190:193], v[114:117]
	v_mfma_f32_16x16x32_bf16 v[110:113], v[166:169], v[200:203], v[110:113]
	v_mfma_f32_16x16x32_bf16 v[106:109], v[174:177], v[200:203], v[106:109]
	v_mfma_f32_16x16x32_bf16 v[102:105], v[166:169], v[208:211], v[102:105]
	v_mfma_f32_16x16x32_bf16 v[98:101], v[174:177], v[208:211], v[98:101]
	v_mfma_f32_16x16x32_bf16 v[126:129], v[170:173], v[186:189], v[126:129]
	v_mfma_f32_16x16x32_bf16 v[122:125], v[178:181], v[186:189], v[122:125]
	v_mfma_f32_16x16x32_bf16 v[118:121], v[170:173], v[196:199], v[118:121]
	v_mfma_f32_16x16x32_bf16 v[114:117], v[178:181], v[196:199], v[114:117]
	v_mfma_f32_16x16x32_bf16 v[110:113], v[170:173], v[204:207], v[110:113]
	v_mfma_f32_16x16x32_bf16 v[106:109], v[178:181], v[204:207], v[106:109]
	v_mfma_f32_16x16x32_bf16 v[102:105], v[170:173], v[212:215], v[102:105]
	v_mfma_f32_16x16x32_bf16 v[98:101], v[178:181], v[212:215], v[98:101]
	s_barrier
	s_setprio 0
	ds_read_b128 v[216:219], v143
	ds_read_b128 v[220:223], v143 offset:1024
	ds_read_b128 v[224:227], v143 offset:2048
	ds_read_b128 v[228:231], v143 offset:3072
	s_add_u32 s28, s25, 0x3400180
	s_addc_u32 s29, s26, 0
	s_add_u32 m0, s98, 0x18000
	global_load_lds_dwordx4 v132, s[28:29]
	s_add_u32 m0, s98, 0x1a000
	global_load_lds_dwordx4 v130, s[28:29]
	s_setprio 1
	s_barrier
	s_waitcnt lgkmcnt(0)
	v_mfma_f32_16x16x32_bf16 v[94:97], v[216:219], v[182:185], v[94:97]
	v_mfma_f32_16x16x32_bf16 v[90:93], v[224:227], v[182:185], v[90:93]
	v_mfma_f32_16x16x32_bf16 v[86:89], v[216:219], v[190:193], v[86:89]
	v_mfma_f32_16x16x32_bf16 v[82:85], v[224:227], v[190:193], v[82:85]
	v_mfma_f32_16x16x32_bf16 v[78:81], v[216:219], v[200:203], v[78:81]
	v_mfma_f32_16x16x32_bf16 v[74:77], v[224:227], v[200:203], v[74:77]
	v_mfma_f32_16x16x32_bf16 v[70:73], v[216:219], v[208:211], v[70:73]
	v_mfma_f32_16x16x32_bf16 v[66:69], v[224:227], v[208:211], v[66:69]
	v_mfma_f32_16x16x32_bf16 v[94:97], v[220:223], v[186:189], v[94:97]
	v_mfma_f32_16x16x32_bf16 v[90:93], v[228:231], v[186:189], v[90:93]
	v_mfma_f32_16x16x32_bf16 v[86:89], v[220:223], v[196:199], v[86:89]
	v_mfma_f32_16x16x32_bf16 v[82:85], v[228:231], v[196:199], v[82:85]
	v_mfma_f32_16x16x32_bf16 v[78:81], v[220:223], v[204:207], v[78:81]
	v_mfma_f32_16x16x32_bf16 v[74:77], v[228:231], v[204:207], v[74:77]
	v_mfma_f32_16x16x32_bf16 v[70:73], v[220:223], v[212:215], v[70:73]
	v_mfma_f32_16x16x32_bf16 v[66:69], v[228:231], v[212:215], v[66:69]
	s_barrier
	s_setprio 0
	ds_read_b128 v[182:185], v141 offset:49152
	ds_read_b128 v[186:189], v141 offset:50176
	ds_read_b128 v[190:193], v139 offset:49152
	ds_read_b128 v[196:199], v139 offset:50176
	ds_read_b128 v[200:203], v137 offset:49152
	ds_read_b128 v[204:207], v137 offset:50176
	ds_read_b128 v[208:211], v135 offset:49152
	ds_read_b128 v[212:215], v135 offset:50176
	s_add_u32 s28, s19, 0x36000180
	s_addc_u32 s29, s24, 0
	s_add_u32 m0, s98, 0x8000
	global_load_lds_dwordx4 v132, s[28:29]
	s_add_u32 m0, s98, 0xa000
	global_load_lds_dwordx4 v130, s[28:29]
	s_setprio 1
	s_barrier
;   #define LDA(dst,b,h) for(int m=0;m<4;++m)for(int k=0;k<2;++k) \
;     dst[m][k]=*reinterpret_cast<const bf16x8*>((char*)SA(b,h)+lds_byte(wr*64+m*16+fr,k*32+fq*8))
;   #define LDB(dst,b,h) for(int n=0;n<2;++n)for(int k=0;k<2;++k) \
;     dst[n][k]=*reinterpret_cast<const bf16x8*>((char*)SB(b,h)+lds_byte(wc*32+n*16+fr,k*32+fq*8))
;   #define MMA(ai,bj,At,Bt_) do{__builtin_amdgcn_s_setprio(1); \
;     for(int m=0;m<4;++m)for(int n=0;n<2;++n)for(int k=0;k<2;++k) \
;       acc[ai][bj][m][n]=__builtin_amdgcn_mfma_f32_16x16x32_bf16(Bt_[n][k],At[m][k],acc[ai][bj][m][n],0,0,0); \
;     __builtin_amdgcn_s_setprio(0);}while(0)
;   #define WAIT_V(n) asm volatile("s_waitcnt vmcnt(" #n ")":::"memory")
;   #define WAIT_L(n) asm volatile("s_waitcnt lgkmcnt(" #n ")":::"memory")
;   #define BAR __builtin_amdgcn_s_barrier()
;   #define SCHED __builtin_amdgcn_sched_barrier(0)
; template <bool TWO, class MID> ...
;     ...
;     BAR; WAIT_L(0); MMA(1,0,At,B0); BAR; SCHED;
;     STAGE_B(SB(1,1),1,t+3);
;     WAIT_V(6); BAR; MMA(1,1,At,B1); BAR;
;   }
;   { LDB(B0,0,0); LDA(At,0,0); STAGE_A(SA(1,1),1,nt-1);
;     BAR; WAIT_L(0); MMA(0,0,At,B0); BAR;
;     LDB(B1,0,1); BAR; WAIT_L(0); MMA(0,1,At,B1); BAR;
;     LDA(At,0,1); WAIT_V(4); BAR; WAIT_L(0); MMA(1,0,At,B0); MMA(1,1,At,B1); BAR; }
	s_waitcnt lgkmcnt(0)
	v_mfma_f32_16x16x32_bf16 v[62:65], v[166:169], v[182:185], v[62:65]
	v_mfma_f32_16x16x32_bf16 v[58:61], v[174:177], v[182:185], v[58:61]
	v_mfma_f32_16x16x32_bf16 v[54:57], v[166:169], v[190:193], v[54:57]
	v_mfma_f32_16x16x32_bf16 v[50:53], v[174:177], v[190:193], v[50:53]
	v_mfma_f32_16x16x32_bf16 v[46:49], v[166:169], v[200:203], v[46:49]
	v_mfma_f32_16x16x32_bf16 v[42:45], v[174:177], v[200:203], v[42:45]
	v_mfma_f32_16x16x32_bf16 v[38:41], v[166:169], v[208:211], v[38:41]
	v_mfma_f32_16x16x32_bf16 v[34:37], v[174:177], v[208:211], v[34:37]
	v_mfma_f32_16x16x32_bf16 v[62:65], v[170:173], v[186:189], v[62:65]
	v_mfma_f32_16x16x32_bf16 v[58:61], v[178:181], v[186:189], v[58:61]
	v_mfma_f32_16x16x32_bf16 v[54:57], v[170:173], v[196:199], v[54:57]
	v_mfma_f32_16x16x32_bf16 v[50:53], v[178:181], v[196:199], v[50:53]
	v_mfma_f32_16x16x32_bf16 v[46:49], v[170:173], v[204:207], v[46:49]
	v_mfma_f32_16x16x32_bf16 v[42:45], v[178:181], v[204:207], v[42:45]
	v_mfma_f32_16x16x32_bf16 v[38:41], v[170:173], v[212:215], v[38:41]
	v_mfma_f32_16x16x32_bf16 v[34:37], v[178:181], v[212:215], v[34:37]
	s_barrier
	s_setprio 0
	s_add_u32 s24, s25, 0x3480180
	s_addc_u32 s25, s26, 0
	s_add_u32 m0, s98, 0x1c000
	global_load_lds_dwordx4 v132, s[24:25]
	s_add_u32 m0, s98, 0x1e000
	global_load_lds_dwordx4 v130, s[24:25]
	s_waitcnt vmcnt(6)
	s_setprio 1
	s_barrier
	v_mfma_f32_16x16x32_bf16 v[30:33], v[216:219], v[182:185], v[30:33]
	v_mfma_f32_16x16x32_bf16 v[26:29], v[224:227], v[182:185], v[26:29]
	v_mfma_f32_16x16x32_bf16 v[22:25], v[216:219], v[190:193], v[22:25]
	v_mfma_f32_16x16x32_bf16 v[18:21], v[224:227], v[190:193], v[18:21]
	v_mfma_f32_16x16x32_bf16 v[14:17], v[216:219], v[200:203], v[14:17]
	v_mfma_f32_16x16x32_bf16 v[10:13], v[224:227], v[200:203], v[10:13]
	v_mfma_f32_16x16x32_bf16 v[6:9], v[216:219], v[208:211], v[6:9]
	v_mfma_f32_16x16x32_bf16 v[2:5], v[224:227], v[208:211], v[2:5]
	v_mfma_f32_16x16x32_bf16 v[30:33], v[220:223], v[186:189], v[30:33]
	v_mfma_f32_16x16x32_bf16 v[26:29], v[228:231], v[186:189], v[26:29]
	v_mfma_f32_16x16x32_bf16 v[22:25], v[220:223], v[196:199], v[22:25]
	v_mfma_f32_16x16x32_bf16 v[18:21], v[228:231], v[196:199], v[18:21]
	v_mfma_f32_16x16x32_bf16 v[14:17], v[220:223], v[204:207], v[14:17]
	v_mfma_f32_16x16x32_bf16 v[10:13], v[228:231], v[204:207], v[10:13]
	v_mfma_f32_16x16x32_bf16 v[6:9], v[220:223], v[212:215], v[6:9]
	v_mfma_f32_16x16x32_bf16 v[2:5], v[228:231], v[212:215], v[2:5]
	s_setprio 0
	s_add_i32 s18, s18, 2
	s_add_u32 s4, s4, 0x100
	s_addc_u32 s5, s5, 0
	s_cmp_lt_u32 s18, 28
	s_barrier
	s_cbranch_scc1 .LBB0_489
	ds_read_b128 v[152:155], v149
	ds_read_b128 v[156:159], v149 offset:1024
	ds_read_b128 v[160:163], v149 offset:2048
	ds_read_b128 v[164:167], v149 offset:3072
	ds_read_b128 v[168:171], v141
	ds_read_b128 v[172:175], v141 offset:1024
	ds_read_b128 v[176:179], v139
	ds_read_b128 v[180:183], v139 offset:1024
	ds_read_b128 v[184:187], v137
	ds_read_b128 v[188:191], v137 offset:1024
	ds_read_b128 v[196:199], v135
	ds_read_b128 v[200:203], v135 offset:1024
	s_add_u32 s4, s12, 0x80f80
	s_addc_u32 s5, s13, 0
	v_lshl_add_u64 v[132:133], s[4:5], 0, v[132:133]
	v_readfirstlane_b32 s12, v148
	s_mov_b32 m0, s12
	global_load_lds_dwordx4 v[132:133], off
	v_lshl_add_u64 v[130:131], s[4:5], 0, v[130:131]
	v_readfirstlane_b32 s4, v150
	s_mov_b32 m0, s4
	global_load_lds_dwordx4 v[130:131], off
	s_setprio 1
	s_barrier
	s_waitcnt lgkmcnt(0)
	v_mfma_f32_16x16x32_bf16 v[126:129], v[152:155], v[168:171], v[126:129]
	v_mfma_f32_16x16x32_bf16 v[122:125], v[160:163], v[168:171], v[122:125]
	v_mfma_f32_16x16x32_bf16 v[118:121], v[152:155], v[176:179], v[118:121]
	v_mfma_f32_16x16x32_bf16 v[114:117], v[160:163], v[176:179], v[114:117]
	v_mfma_f32_16x16x32_bf16 v[102:105], v[152:155], v[196:199], v[102:105]
	v_mfma_f32_16x16x32_bf16 v[98:101], v[160:163], v[196:199], v[98:101]
	v_mfma_f32_16x16x32_bf16 v[126:129], v[156:159], v[172:175], v[126:129]
	v_mfma_f32_16x16x32_bf16 v[122:125], v[164:167], v[172:175], v[122:125]
	v_mfma_f32_16x16x32_bf16 v[118:121], v[156:159], v[180:183], v[118:121]
	v_mfma_f32_16x16x32_bf16 v[114:117], v[164:167], v[180:183], v[114:117]
	v_mfma_f32_16x16x32_bf16 v[110:113], v[152:155], v[184:187], v[110:113]
	v_mfma_f32_16x16x32_bf16 v[106:109], v[160:163], v[184:187], v[106:109]
	v_mfma_f32_16x16x32_bf16 v[102:105], v[156:159], v[200:203], v[102:105]
	v_mfma_f32_16x16x32_bf16 v[98:101], v[164:167], v[200:203], v[98:101]
	v_mfma_f32_16x16x32_bf16 v[130:133], v[156:159], v[188:191], v[110:113]
	v_mfma_f32_16x16x32_bf16 v[148:151], v[164:167], v[188:191], v[106:109]
	s_barrier
	s_setprio 0
	s_nop 0
	ds_read_b128 v[106:109], v147
	ds_read_b128 v[110:113], v147 offset:1024
	ds_read_b128 v[204:207], v147 offset:2048
	ds_read_b128 v[208:211], v147 offset:3072
	s_setprio 1
	s_barrier
	s_waitcnt lgkmcnt(0)
	v_mfma_f32_16x16x32_bf16 v[86:89], v[106:109], v[176:179], v[86:89]
	v_mfma_f32_16x16x32_bf16 v[82:85], v[204:207], v[176:179], v[82:85]
	v_mfma_f32_16x16x32_bf16 v[70:73], v[106:109], v[196:199], v[70:73]
	v_mfma_f32_16x16x32_bf16 v[66:69], v[204:207], v[196:199], v[66:69]
	v_mfma_f32_16x16x32_bf16 v[94:97], v[106:109], v[168:171], v[94:97]
	v_mfma_f32_16x16x32_bf16 v[90:93], v[204:207], v[168:171], v[90:93]
	v_mfma_f32_16x16x32_bf16 v[86:89], v[110:113], v[180:183], v[86:89]
	v_mfma_f32_16x16x32_bf16 v[82:85], v[208:211], v[180:183], v[82:85]
	v_mfma_f32_16x16x32_bf16 v[78:81], v[106:109], v[184:187], v[78:81]
	v_mfma_f32_16x16x32_bf16 v[74:77], v[204:207], v[184:187], v[74:77]
	v_mfma_f32_16x16x32_bf16 v[70:73], v[110:113], v[200:203], v[70:73]
	v_mfma_f32_16x16x32_bf16 v[66:69], v[208:211], v[200:203], v[66:69]
	v_mfma_f32_16x16x32_bf16 v[212:215], v[110:113], v[172:175], v[94:97]
	v_mfma_f32_16x16x32_bf16 v[168:171], v[208:211], v[172:175], v[90:93]
	v_mfma_f32_16x16x32_bf16 v[172:175], v[110:113], v[188:191], v[78:81]
	v_mfma_f32_16x16x32_bf16 v[176:179], v[208:211], v[188:191], v[74:77]
	s_barrier
;   #define LDA(dst,b,h) for(int m=0;m<4;++m)for(int k=0;k<2;++k) \
;     dst[m][k]=*reinterpret_cast<const bf16x8*>((char*)SA(b,h)+lds_byte(wr*64+m*16+fr,k*32+fq*8))
;   #define LDB(dst,b,h) for(int n=0;n<2;++n)for(int k=0;k<2;++k) \
;     dst[n][k]=*reinterpret_cast<const bf16x8*>((char*)SB(b,h)+lds_byte(wc*32+n*16+fr,k*32+fq*8))
;   #define MMA(ai,bj,At,Bt_) do{__builtin_amdgcn_s_setprio(1); \
;     for(int m=0;m<4;++m)for(int n=0;n<2;++n)for(int k=0;k<2;++k) \
;       acc[ai][bj][m][n]=__builtin_amdgcn_mfma_f32_16x16x32_bf16(Bt_[n][k],At[m][k],acc[ai][bj][m][n],0,0,0); \
;     __builtin_amdgcn_s_setprio(0);}while(0)
;   #define WAIT_V(n) asm volatile("s_waitcnt vmcnt(" #n ")":::"memory")
;   #define WAIT_L(n) asm volatile("s_waitcnt lgkmcnt(" #n ")":::"memory")
;   #define BAR __builtin_amdgcn_s_barrier()
; template <bool TWO, class MID> ...
;     ...
;     LDA(At,0,1); WAIT_V(4); BAR; WAIT_L(0); MMA(1,0,At,B0); MMA(1,1,At,B1); BAR; }
;   { LDB(B0,1,0); LDA(At,1,0); WAIT_V(2); BAR; WAIT_L(0); MMA(0,0,At,B0); BAR;
	s_setprio 0
	s_nop 0
	ds_read_b128 v[74:77], v141 offset:16384
	ds_read_b128 v[78:81], v141 offset:17408
	ds_read_b128 v[90:93], v139 offset:16384
	ds_read_b128 v[94:97], v139 offset:17408
	ds_read_b128 v[180:183], v137 offset:16384
	ds_read_b128 v[184:187], v137 offset:17408
	ds_read_b128 v[188:191], v135 offset:16384
	ds_read_b128 v[196:199], v135 offset:17408
	s_waitcnt vmcnt(4)
	s_setprio 1
	s_barrier
	s_waitcnt lgkmcnt(0)
	v_mfma_f32_16x16x32_bf16 v[62:65], v[152:155], v[74:77], v[62:65]
	v_mfma_f32_16x16x32_bf16 v[58:61], v[160:163], v[74:77], v[58:61]
	v_mfma_f32_16x16x32_bf16 v[54:57], v[152:155], v[90:93], v[54:57]
	v_mfma_f32_16x16x32_bf16 v[50:53], v[160:163], v[90:93], v[50:53]
	v_mfma_f32_16x16x32_bf16 v[38:41], v[152:155], v[188:191], v[38:41]
	v_mfma_f32_16x16x32_bf16 v[34:37], v[160:163], v[188:191], v[34:37]
	v_mfma_f32_16x16x32_bf16 v[62:65], v[156:159], v[78:81], v[62:65]
	v_mfma_f32_16x16x32_bf16 v[58:61], v[164:167], v[78:81], v[58:61]
	v_mfma_f32_16x16x32_bf16 v[54:57], v[156:159], v[94:97], v[54:57]
	v_mfma_f32_16x16x32_bf16 v[50:53], v[164:167], v[94:97], v[50:53]
	v_mfma_f32_16x16x32_bf16 v[46:49], v[152:155], v[180:183], v[46:49]
	v_mfma_f32_16x16x32_bf16 v[42:45], v[160:163], v[180:183], v[42:45]
	v_mfma_f32_16x16x32_bf16 v[38:41], v[156:159], v[196:199], v[38:41]
	v_mfma_f32_16x16x32_bf16 v[34:37], v[164:167], v[196:199], v[34:37]
	v_mfma_f32_16x16x32_bf16 v[200:203], v[156:159], v[184:187], v[46:49]
	v_mfma_f32_16x16x32_bf16 v[216:219], v[164:167], v[184:187], v[42:45]
	s_setprio 0
	s_setprio 1
	v_mfma_f32_16x16x32_bf16 v[22:25], v[106:109], v[90:93], v[22:25]
	v_mfma_f32_16x16x32_bf16 v[18:21], v[204:207], v[90:93], v[18:21]
	v_mfma_f32_16x16x32_bf16 v[6:9], v[106:109], v[188:191], v[6:9]
	v_mfma_f32_16x16x32_bf16 v[2:5], v[204:207], v[188:191], v[2:5]
	v_mfma_f32_16x16x32_bf16 v[30:33], v[106:109], v[74:77], v[30:33]
	v_mfma_f32_16x16x32_bf16 v[26:29], v[204:207], v[74:77], v[26:29]
	v_mfma_f32_16x16x32_bf16 v[22:25], v[110:113], v[94:97], v[22:25]
	v_mfma_f32_16x16x32_bf16 v[18:21], v[208:211], v[94:97], v[18:21]
	v_mfma_f32_16x16x32_bf16 v[14:17], v[106:109], v[180:183], v[14:17]
	v_mfma_f32_16x16x32_bf16 v[10:13], v[204:207], v[180:183], v[10:13]
	v_mfma_f32_16x16x32_bf16 v[6:9], v[110:113], v[196:199], v[6:9]
	v_mfma_f32_16x16x32_bf16 v[2:5], v[208:211], v[196:199], v[2:5]
	v_mfma_f32_16x16x32_bf16 v[152:155], v[110:113], v[78:81], v[30:33]
	v_mfma_f32_16x16x32_bf16 v[156:159], v[208:211], v[78:81], v[26:29]
	v_mfma_f32_16x16x32_bf16 v[160:163], v[110:113], v[184:187], v[14:17]
	v_mfma_f32_16x16x32_bf16 v[164:167], v[208:211], v[184:187], v[10:13]
	s_barrier
	s_setprio 0
	s_nop 0
	ds_read_b128 v[10:13], v145
	ds_read_b128 v[14:17], v145 offset:1024
	ds_read_b128 v[180:183], v145 offset:2048
	ds_read_b128 v[144:147], v145 offset:3072
	ds_read_b128 v[26:29], v141 offset:32768
	ds_read_b128 v[30:33], v141 offset:33792
	ds_read_b128 v[42:45], v139 offset:32768
	ds_read_b128 v[46:49], v139 offset:33792
	ds_read_b128 v[184:187], v137 offset:32768
	ds_read_b128 v[188:191], v137 offset:33792
	ds_read_b128 v[196:199], v135 offset:32768
	ds_read_b128 v[204:207], v135 offset:33792
	s_waitcnt vmcnt(2)
	s_setprio 1
	s_barrier
	s_waitcnt lgkmcnt(0)
	v_mfma_f32_16x16x32_bf16 v[74:77], v[10:13], v[26:29], v[126:129]
	v_mfma_f32_16x16x32_bf16 v[126:129], v[14:17], v[30:33], v[74:77]
	v_mfma_f32_16x16x32_bf16 v[74:77], v[180:183], v[26:29], v[122:125]
	v_mfma_f32_16x16x32_bf16 v[122:125], v[144:147], v[30:33], v[74:77]
	v_mfma_f32_16x16x32_bf16 v[74:77], v[10:13], v[42:45], v[118:121]
	v_mfma_f32_16x16x32_bf16 v[110:113], v[14:17], v[46:49], v[74:77]
	v_mfma_f32_16x16x32_bf16 v[74:77], v[180:183], v[42:45], v[114:117]
	v_mfma_f32_16x16x32_bf16 v[106:109], v[144:147], v[46:49], v[74:77]
	v_mfma_f32_16x16x32_bf16 v[74:77], v[10:13], v[184:187], v[130:133]
	v_mfma_f32_16x16x32_bf16 v[94:97], v[14:17], v[188:191], v[74:77]
	v_mfma_f32_16x16x32_bf16 v[74:77], v[180:183], v[184:187], v[148:151]
	v_mfma_f32_16x16x32_bf16 v[90:93], v[144:147], v[188:191], v[74:77]
	v_mfma_f32_16x16x32_bf16 v[74:77], v[10:13], v[196:199], v[102:105]
	v_mfma_f32_16x16x32_bf16 v[78:81], v[14:17], v[204:207], v[74:77]
	v_mfma_f32_16x16x32_bf16 v[74:77], v[180:183], v[196:199], v[98:101]
	v_mfma_f32_16x16x32_bf16 v[74:77], v[144:147], v[204:207], v[74:77]
	s_barrier
;   #define LDA(dst,b,h) for(int m=0;m<4;++m)for(int k=0;k<2;++k) \
;     dst[m][k]=*reinterpret_cast<const bf16x8*>((char*)SA(b,h)+lds_byte(wr*64+m*16+fr,k*32+fq*8))
;   #define LDB(dst,b,h) for(int n=0;n<2;++n)for(int k=0;k<2;++k) \
;     dst[n][k]=*reinterpret_cast<const bf16x8*>((char*)SB(b,h)+lds_byte(wc*32+n*16+fr,k*32+fq*8))
;   #define MMA(ai,bj,At,Bt_) do{__builtin_amdgcn_s_setprio(1); \
;     for(int m=0;m<4;++m)for(int n=0;n<2;++n)for(int k=0;k<2;++k) \
;       acc[ai][bj][m][n]=__builtin_amdgcn_mfma_f32_16x16x32_bf16(Bt_[n][k],At[m][k],acc[ai][bj][m][n],0,0,0); \
;     __builtin_amdgcn_s_setprio(0);}while(0)
;   #define WAIT_V(n) asm volatile("s_waitcnt vmcnt(" #n ")":::"memory")
;   #define WAIT_L(n) asm volatile("s_waitcnt lgkmcnt(" #n ")":::"memory")
;   #define BAR __builtin_amdgcn_s_barrier()
; template <bool TWO, class MID> ...
;     ...
;     LDB(B1,1,1); WAIT_V(0); BAR; WAIT_L(0); MMA(0,1,At,B1); BAR;
;     LDA(At,1,1); BAR; WAIT_L(0); MMA(1,0,At,B0); MMA(1,1,At,B1); BAR; }
;   if(wr==0)BAR;
	s_setprio 0
	ds_read_b128 v[130:133], v143
	ds_read_b128 v[148:151], v143 offset:1024
	ds_read_b128 v[208:211], v143 offset:2048
	ds_read_b128 v[220:223], v143 offset:3072
	s_waitcnt vmcnt(0)
	s_setprio 1
	s_barrier
	s_waitcnt lgkmcnt(0)
	v_mfma_f32_16x16x32_bf16 v[98:101], v[130:133], v[26:29], v[212:215]
	v_mfma_f32_16x16x32_bf16 v[26:29], v[208:211], v[26:29], v[168:171]
	v_mfma_f32_16x16x32_bf16 v[114:117], v[220:223], v[30:33], v[26:29]
	v_mfma_f32_16x16x32_bf16 v[26:29], v[130:133], v[42:45], v[86:89]
	v_mfma_f32_16x16x32_bf16 v[102:105], v[148:151], v[46:49], v[26:29]
	v_mfma_f32_16x16x32_bf16 v[26:29], v[208:211], v[42:45], v[82:85]
	v_mfma_f32_16x16x32_bf16 v[118:121], v[148:151], v[30:33], v[98:101]
	v_mfma_f32_16x16x32_bf16 v[98:101], v[220:223], v[46:49], v[26:29]
	v_mfma_f32_16x16x32_bf16 v[26:29], v[130:133], v[184:187], v[172:175]
	v_mfma_f32_16x16x32_bf16 v[86:89], v[148:151], v[188:191], v[26:29]
	v_mfma_f32_16x16x32_bf16 v[26:29], v[208:211], v[184:187], v[176:179]
	v_mfma_f32_16x16x32_bf16 v[82:85], v[220:223], v[188:191], v[26:29]
	v_mfma_f32_16x16x32_bf16 v[26:29], v[130:133], v[196:199], v[70:73]
	v_mfma_f32_16x16x32_bf16 v[70:73], v[148:151], v[204:207], v[26:29]
	v_mfma_f32_16x16x32_bf16 v[26:29], v[208:211], v[196:199], v[66:69]
	v_mfma_f32_16x16x32_bf16 v[66:69], v[220:223], v[204:207], v[26:29]
	s_barrier
	s_setprio 0
	ds_read_b128 v[168:171], v141 offset:49152
	ds_read_b128 v[140:143], v141 offset:50176
	ds_read_b128 v[172:175], v139 offset:49152
	ds_read_b128 v[176:179], v139 offset:50176
	ds_read_b128 v[184:187], v137 offset:49152
	ds_read_b128 v[136:139], v137 offset:50176
	ds_read_b128 v[188:191], v135 offset:49152
	ds_read_b128 v[196:199], v135 offset:50176
	s_setprio 1
	s_barrier
	s_waitcnt lgkmcnt(0)
	v_mfma_f32_16x16x32_bf16 v[26:29], v[10:13], v[168:171], v[62:65]
	v_mfma_f32_16x16x32_bf16 v[62:65], v[14:17], v[140:143], v[26:29]
	v_mfma_f32_16x16x32_bf16 v[26:29], v[180:183], v[168:171], v[58:61]
	v_mfma_f32_16x16x32_bf16 v[58:61], v[144:147], v[140:143], v[26:29]
	v_mfma_f32_16x16x32_bf16 v[26:29], v[10:13], v[172:175], v[54:57]
	v_mfma_f32_16x16x32_bf16 v[46:49], v[14:17], v[176:179], v[26:29]
	v_mfma_f32_16x16x32_bf16 v[26:29], v[180:183], v[172:175], v[50:53]
	v_mfma_f32_16x16x32_bf16 v[42:45], v[144:147], v[176:179], v[26:29]
	v_mfma_f32_16x16x32_bf16 v[26:29], v[10:13], v[184:187], v[200:203]
	v_mfma_f32_16x16x32_bf16 v[10:13], v[10:13], v[188:191], v[38:41]
	v_mfma_f32_16x16x32_bf16 v[30:33], v[14:17], v[136:139], v[26:29]
	v_mfma_f32_16x16x32_bf16 v[26:29], v[180:183], v[184:187], v[216:219]
	v_mfma_f32_16x16x32_bf16 v[14:17], v[14:17], v[196:199], v[10:13]
	v_mfma_f32_16x16x32_bf16 v[10:13], v[180:183], v[188:191], v[34:37]
	v_mfma_f32_16x16x32_bf16 v[26:29], v[144:147], v[136:139], v[26:29]
	v_mfma_f32_16x16x32_bf16 v[10:13], v[144:147], v[196:199], v[10:13]
	s_setprio 0
	s_setprio 1
	v_mfma_f32_16x16x32_bf16 v[34:37], v[130:133], v[168:171], v[152:155]
	v_mfma_f32_16x16x32_bf16 v[54:57], v[148:151], v[140:143], v[34:37]
	v_mfma_f32_16x16x32_bf16 v[34:37], v[208:211], v[168:171], v[156:159]
	v_mfma_f32_16x16x32_bf16 v[18:21], v[208:211], v[172:175], v[18:21]
	v_mfma_f32_16x16x32_bf16 v[50:53], v[220:223], v[140:143], v[34:37]
	v_mfma_f32_16x16x32_bf16 v[22:25], v[130:133], v[172:175], v[22:25]
	v_mfma_f32_16x16x32_bf16 v[34:37], v[220:223], v[176:179], v[18:21]
	v_mfma_f32_16x16x32_bf16 v[18:21], v[130:133], v[184:187], v[160:163]
	v_mfma_f32_16x16x32_bf16 v[38:41], v[148:151], v[176:179], v[22:25]
	v_mfma_f32_16x16x32_bf16 v[22:25], v[148:151], v[136:139], v[18:21]
	v_mfma_f32_16x16x32_bf16 v[18:21], v[208:211], v[184:187], v[164:167]
	v_mfma_f32_16x16x32_bf16 v[6:9], v[130:133], v[188:191], v[6:9]
	v_mfma_f32_16x16x32_bf16 v[2:5], v[208:211], v[188:191], v[2:5]
	v_mfma_f32_16x16x32_bf16 v[18:21], v[220:223], v[136:139], v[18:21]
	v_mfma_f32_16x16x32_bf16 v[6:9], v[148:151], v[196:199], v[6:9]
	v_mfma_f32_16x16x32_bf16 v[2:5], v[220:223], v[196:199], v[2:5]
	s_setprio 0
	v_cmp_gt_u32_e32 vcc, s30, v1
	s_barrier
	s_and_saveexec_b64 s[4:5], vcc
	s_cbranch_execz .LBB0_492
	s_barrier

;   #define LDA(dst,b,h) for(int m=0;m<4;++m)for(int k=0;k<2;++k) \
;     dst[m][k]=*reinterpret_cast<const bf16x8*>((char*)SA(b,h)+lds_byte(wr*64+m*16+fr,k*32+fq*8))
;   #define LDB(dst,b,h) for(int n=0;n<2;++n)for(int k=0;k<2;++k) \
;     dst[n][k]=*reinterpret_cast<const bf16x8*>((char*)SB(b,h)+lds_byte(wc*32+n*16+fr,k*32+fq*8))
;   #define MMA(ai,bj,At,Bt_) do{__builtin_amdgcn_s_setprio(1); \
;     for(int m=0;m<4;++m)for(int n=0;n<2;++n)for(int k=0;k<2;++k) \
;       acc[ai][bj][m][n]=__builtin_amdgcn_mfma_f32_16x16x32_bf16(Bt_[n][k],At[m][k],acc[ai][bj][m][n],0,0,0); \
;     __builtin_amdgcn_s_setprio(0);}while(0)
;   #define WAIT_V(n) asm volatile("s_waitcnt vmcnt(" #n ")":::"memory")
;   #define WAIT_L(n) asm volatile("s_waitcnt lgkmcnt(" #n ")":::"memory")
;   #define BAR __builtin_amdgcn_s_barrier()
;   #define SCHED __builtin_amdgcn_sched_barrier(0)
; template <bool TWO, class MID> ...
;     ...
;   for(int t=0;t<nt-2;t+=2){
;     if (TWO && t == nt1) mid();
;     LDB(B0,0,0); SCHED; LDA(At,0,0); STAGE_A(SA(1,1),1,t+1);
;     WAIT_L(8); BAR; WAIT_L(0); MMA(0,0,At,B0); BAR; SCHED;
;     LDB(B1,0,1); STAGE_B(SB(0,0),0,t+2);
;     BAR; WAIT_L(0); MMA(0,1,At,B1); BAR;
;     LDA(At,0,1); STAGE_A(SA(0,0),0,t+2);
;     BAR; WAIT_L(0); MMA(1,0,At,B0); BAR; SCHED;
;     STAGE_B(SB(0,1),1,t+2);
;     WAIT_V(6); BAR; MMA(1,1,At,B1); BAR;
.LBB0_562:
	ds_read_b128 v[166:169], v149
	ds_read_b128 v[170:173], v149 offset:1024
	ds_read_b128 v[174:177], v149 offset:2048
	ds_read_b128 v[178:181], v149 offset:3072
	ds_read_b128 v[182:185], v141
	ds_read_b128 v[186:189], v141 offset:1024
	ds_read_b128 v[190:193], v139
	ds_read_b128 v[196:199], v139 offset:1024
	ds_read_b128 v[200:203], v137
	ds_read_b128 v[204:207], v137 offset:1024
	ds_read_b128 v[208:211], v135
	ds_read_b128 v[212:215], v135 offset:1024
	s_add_u32 s23, s4, s12
	s_addc_u32 s24, s5, s13
	s_add_u32 s26, s23, 0x8080080
	s_addc_u32 s27, s24, 0
	s_add_u32 m0, s98, 0xc000
	global_load_lds_dwordx4 v132, s[26:27]
	s_add_u32 m0, s98, 0xe000
	global_load_lds_dwordx4 v130, s[26:27]
	s_waitcnt lgkmcnt(8)
	s_setprio 1
	s_barrier
	s_waitcnt lgkmcnt(0)
	v_mfma_f32_16x16x32_bf16 v[126:129], v[166:169], v[182:185], v[126:129]
	v_mfma_f32_16x16x32_bf16 v[122:125], v[174:177], v[182:185], v[122:125]
	v_mfma_f32_16x16x32_bf16 v[118:121], v[166:169], v[190:193], v[118:121]
	v_mfma_f32_16x16x32_bf16 v[114:117], v[174:177], v[190:193], v[114:117]
	v_mfma_f32_16x16x32_bf16 v[110:113], v[166:169], v[200:203], v[110:113]
	v_mfma_f32_16x16x32_bf16 v[106:109], v[174:177], v[200:203], v[106:109]
	v_mfma_f32_16x16x32_bf16 v[102:105], v[166:169], v[208:211], v[102:105]
	v_mfma_f32_16x16x32_bf16 v[98:101], v[174:177], v[208:211], v[98:101]
	v_mfma_f32_16x16x32_bf16 v[126:129], v[170:173], v[186:189], v[126:129]
	v_mfma_f32_16x16x32_bf16 v[122:125], v[178:181], v[186:189], v[122:125]
	v_mfma_f32_16x16x32_bf16 v[118:121], v[170:173], v[196:199], v[118:121]
	v_mfma_f32_16x16x32_bf16 v[114:117], v[178:181], v[196:199], v[114:117]
	v_mfma_f32_16x16x32_bf16 v[110:113], v[170:173], v[204:207], v[110:113]
	v_mfma_f32_16x16x32_bf16 v[106:109], v[178:181], v[204:207], v[106:109]
	v_mfma_f32_16x16x32_bf16 v[102:105], v[170:173], v[212:215], v[102:105]
	v_mfma_f32_16x16x32_bf16 v[98:101], v[178:181], v[212:215], v[98:101]
	s_barrier
	s_setprio 0
	s_add_u32 s25, s4, s14
	ds_read_b128 v[216:219], v147
	ds_read_b128 v[220:223], v147 offset:1024
	ds_read_b128 v[224:227], v147 offset:2048
	ds_read_b128 v[228:231], v147 offset:3072
	s_addc_u32 s26, s5, s15
	s_add_u32 s28, s25, 0x3c00100
	s_addc_u32 s29, s26, 0
	s_add_u32 m0, s98, 0x10000
	global_load_lds_dwordx4 v132, s[28:29]
	s_add_u32 m0, s98, 0x12000
	global_load_lds_dwordx4 v130, s[28:29]
	s_setprio 1
	s_barrier
	s_waitcnt lgkmcnt(0)
	v_mfma_f32_16x16x32_bf16 v[94:97], v[216:219], v[182:185], v[94:97]
	v_mfma_f32_16x16x32_bf16 v[90:93], v[224:227], v[182:185], v[90:93]
	v_mfma_f32_16x16x32_bf16 v[86:89], v[216:219], v[190:193], v[86:89]
	v_mfma_f32_16x16x32_bf16 v[82:85], v[224:227], v[190:193], v[82:85]
	v_mfma_f32_16x16x32_bf16 v[78:81], v[216:219], v[200:203], v[78:81]
	v_mfma_f32_16x16x32_bf16 v[74:77], v[224:227], v[200:203], v[74:77]
	v_mfma_f32_16x16x32_bf16 v[70:73], v[216:219], v[208:211], v[70:73]
	v_mfma_f32_16x16x32_bf16 v[66:69], v[224:227], v[208:211], v[66:69]
	v_mfma_f32_16x16x32_bf16 v[94:97], v[220:223], v[186:189], v[94:97]
	v_mfma_f32_16x16x32_bf16 v[90:93], v[228:231], v[186:189], v[90:93]
	v_mfma_f32_16x16x32_bf16 v[86:89], v[220:223], v[196:199], v[86:89]
	v_mfma_f32_16x16x32_bf16 v[82:85], v[228:231], v[196:199], v[82:85]
	v_mfma_f32_16x16x32_bf16 v[78:81], v[220:223], v[204:207], v[78:81]
	v_mfma_f32_16x16x32_bf16 v[74:77], v[228:231], v[204:207], v[74:77]
	v_mfma_f32_16x16x32_bf16 v[70:73], v[220:223], v[212:215], v[70:73]
	v_mfma_f32_16x16x32_bf16 v[66:69], v[228:231], v[212:215], v[66:69]
	s_barrier
	s_setprio 0
	ds_read_b128 v[182:185], v141 offset:16384
	ds_read_b128 v[186:189], v141 offset:17408
	ds_read_b128 v[190:193], v139 offset:16384
	ds_read_b128 v[196:199], v139 offset:17408
	ds_read_b128 v[200:203], v137 offset:16384
	ds_read_b128 v[204:207], v137 offset:17408
	ds_read_b128 v[208:211], v135 offset:16384
	ds_read_b128 v[212:215], v135 offset:17408
	s_add_u32 s28, s23, 0x8000100
	s_addc_u32 s29, s24, 0
	s_add_u32 m0, s98, 0x0
	global_load_lds_dwordx4 v132, s[28:29]
	s_add_u32 m0, s98, 0x2000
	global_load_lds_dwordx4 v130, s[28:29]
	s_setprio 1
	s_barrier
	s_waitcnt lgkmcnt(0)
	v_mfma_f32_16x16x32_bf16 v[62:65], v[166:169], v[182:185], v[62:65]
	v_mfma_f32_16x16x32_bf16 v[58:61], v[174:177], v[182:185], v[58:61]
	v_mfma_f32_16x16x32_bf16 v[54:57], v[166:169], v[190:193], v[54:57]
	v_mfma_f32_16x16x32_bf16 v[50:53], v[174:177], v[190:193], v[50:53]
	v_mfma_f32_16x16x32_bf16 v[46:49], v[166:169], v[200:203], v[46:49]
	v_mfma_f32_16x16x32_bf16 v[42:45], v[174:177], v[200:203], v[42:45]
	v_mfma_f32_16x16x32_bf16 v[38:41], v[166:169], v[208:211], v[38:41]
	v_mfma_f32_16x16x32_bf16 v[34:37], v[174:177], v[208:211], v[34:37]
	v_mfma_f32_16x16x32_bf16 v[62:65], v[170:173], v[186:189], v[62:65]
	v_mfma_f32_16x16x32_bf16 v[58:61], v[178:181], v[186:189], v[58:61]
	v_mfma_f32_16x16x32_bf16 v[54:57], v[170:173], v[196:199], v[54:57]
	v_mfma_f32_16x16x32_bf16 v[50:53], v[178:181], v[196:199], v[50:53]
	v_mfma_f32_16x16x32_bf16 v[46:49], v[170:173], v[204:207], v[46:49]
	v_mfma_f32_16x16x32_bf16 v[42:45], v[178:181], v[204:207], v[42:45]
	v_mfma_f32_16x16x32_bf16 v[38:41], v[170:173], v[212:215], v[38:41]
	v_mfma_f32_16x16x32_bf16 v[34:37], v[178:181], v[212:215], v[34:37]
	s_barrier
	s_setprio 0
	s_add_u32 s28, s25, 0x3c80100
	s_addc_u32 s29, s26, 0
	s_add_u32 m0, s98, 0x14000
	global_load_lds_dwordx4 v132, s[28:29]
	s_add_u32 m0, s98, 0x16000
	global_load_lds_dwordx4 v130, s[28:29]
	s_waitcnt vmcnt(6)
	s_setprio 1
	s_barrier
;   #define LDA(dst,b,h) for(int m=0;m<4;++m)for(int k=0;k<2;++k) \
;     dst[m][k]=*reinterpret_cast<const bf16x8*>((char*)SA(b,h)+lds_byte(wr*64+m*16+fr,k*32+fq*8))
;   #define LDB(dst,b,h) for(int n=0;n<2;++n)for(int k=0;k<2;++k) \
;     dst[n][k]=*reinterpret_cast<const bf16x8*>((char*)SB(b,h)+lds_byte(wc*32+n*16+fr,k*32+fq*8))
;   #define MMA(ai,bj,At,Bt_) do{__builtin_amdgcn_s_setprio(1); \
;     for(int m=0;m<4;++m)for(int n=0;n<2;++n)for(int k=0;k<2;++k) \
;       acc[ai][bj][m][n]=__builtin_amdgcn_mfma_f32_16x16x32_bf16(Bt_[n][k],At[m][k],acc[ai][bj][m][n],0,0,0); \
;     __builtin_amdgcn_s_setprio(0);}while(0)
;   #define WAIT_V(n) asm volatile("s_waitcnt vmcnt(" #n ")":::"memory")
;   #define WAIT_L(n) asm volatile("s_waitcnt lgkmcnt(" #n ")":::"memory")
;   #define BAR __builtin_amdgcn_s_barrier()
;   #define SCHED __builtin_amdgcn_sched_barrier(0)
; template <bool TWO, class MID> ...
;     ...
;     WAIT_V(6); BAR; MMA(1,1,At,B1); BAR;
;     LDB(B0,1,0); SCHED; LDA(At,1,0); STAGE_A(SA(0,1),1,t+2);
;     WAIT_L(8); BAR; WAIT_L(0); MMA(0,0,At,B0); BAR; SCHED;
;     LDB(B1,1,1); STAGE_B(SB(1,0),0,t+3);
;     BAR; WAIT_L(0); MMA(0,1,At,B1); BAR;
;     LDA(At,1,1); STAGE_A(SA(1,0),0,t+3);
;     BAR; WAIT_L(0); MMA(1,0,At,B0); BAR; SCHED;
	v_mfma_f32_16x16x32_bf16 v[30:33], v[216:219], v[182:185], v[30:33]
	v_mfma_f32_16x16x32_bf16 v[26:29], v[224:227], v[182:185], v[26:29]
	ds_read_b128 v[166:169], v145
	v_mfma_f32_16x16x32_bf16 v[22:25], v[216:219], v[190:193], v[22:25]
	v_mfma_f32_16x16x32_bf16 v[18:21], v[224:227], v[190:193], v[18:21]
	ds_read_b128 v[170:173], v145 offset:1024
	v_mfma_f32_16x16x32_bf16 v[14:17], v[216:219], v[200:203], v[14:17]
	v_mfma_f32_16x16x32_bf16 v[10:13], v[224:227], v[200:203], v[10:13]
	ds_read_b128 v[174:177], v145 offset:2048
	v_mfma_f32_16x16x32_bf16 v[6:9], v[216:219], v[208:211], v[6:9]
	v_mfma_f32_16x16x32_bf16 v[2:5], v[224:227], v[208:211], v[2:5]
	ds_read_b128 v[178:181], v145 offset:3072
	v_mfma_f32_16x16x32_bf16 v[30:33], v[220:223], v[186:189], v[30:33]
	v_mfma_f32_16x16x32_bf16 v[26:29], v[228:231], v[186:189], v[26:29]
	v_mfma_f32_16x16x32_bf16 v[22:25], v[220:223], v[196:199], v[22:25]
	v_mfma_f32_16x16x32_bf16 v[18:21], v[228:231], v[196:199], v[18:21]
	v_mfma_f32_16x16x32_bf16 v[14:17], v[220:223], v[204:207], v[14:17]
	v_mfma_f32_16x16x32_bf16 v[10:13], v[228:231], v[204:207], v[10:13]
	v_mfma_f32_16x16x32_bf16 v[6:9], v[220:223], v[212:215], v[6:9]
	v_mfma_f32_16x16x32_bf16 v[2:5], v[228:231], v[212:215], v[2:5]
	s_barrier
	s_setprio 0
	ds_read_b128 v[182:185], v141 offset:32768
	ds_read_b128 v[186:189], v141 offset:33792
	ds_read_b128 v[190:193], v139 offset:32768
	ds_read_b128 v[196:199], v139 offset:33792
	ds_read_b128 v[200:203], v137 offset:32768
	ds_read_b128 v[204:207], v137 offset:33792
	ds_read_b128 v[208:211], v135 offset:32768
	ds_read_b128 v[212:215], v135 offset:33792
	s_add_u32 s28, s23, 0x8080100
	s_addc_u32 s29, s24, 0
	s_add_u32 m0, s98, 0x4000
	global_load_lds_dwordx4 v132, s[28:29]
	s_add_u32 m0, s98, 0x6000
	global_load_lds_dwordx4 v130, s[28:29]
	s_waitcnt lgkmcnt(8)
	s_setprio 1
	s_barrier
	s_waitcnt lgkmcnt(0)
	v_mfma_f32_16x16x32_bf16 v[126:129], v[166:169], v[182:185], v[126:129]
	v_mfma_f32_16x16x32_bf16 v[122:125], v[174:177], v[182:185], v[122:125]
	v_mfma_f32_16x16x32_bf16 v[118:121], v[166:169], v[190:193], v[118:121]
	v_mfma_f32_16x16x32_bf16 v[114:117], v[174:177], v[190:193], v[114:117]
	v_mfma_f32_16x16x32_bf16 v[110:113], v[166:169], v[200:203], v[110:113]
	v_mfma_f32_16x16x32_bf16 v[106:109], v[174:177], v[200:203], v[106:109]
	v_mfma_f32_16x16x32_bf16 v[102:105], v[166:169], v[208:211], v[102:105]
	v_mfma_f32_16x16x32_bf16 v[98:101], v[174:177], v[208:211], v[98:101]
	v_mfma_f32_16x16x32_bf16 v[126:129], v[170:173], v[186:189], v[126:129]
	v_mfma_f32_16x16x32_bf16 v[122:125], v[178:181], v[186:189], v[122:125]
	v_mfma_f32_16x16x32_bf16 v[118:121], v[170:173], v[196:199], v[118:121]
	v_mfma_f32_16x16x32_bf16 v[114:117], v[178:181], v[196:199], v[114:117]
	v_mfma_f32_16x16x32_bf16 v[110:113], v[170:173], v[204:207], v[110:113]
	v_mfma_f32_16x16x32_bf16 v[106:109], v[178:181], v[204:207], v[106:109]
	v_mfma_f32_16x16x32_bf16 v[102:105], v[170:173], v[212:215], v[102:105]
	v_mfma_f32_16x16x32_bf16 v[98:101], v[178:181], v[212:215], v[98:101]
	s_barrier
	s_setprio 0
	ds_read_b128 v[216:219], v143
	ds_read_b128 v[220:223], v143 offset:1024
	ds_read_b128 v[224:227], v143 offset:2048
	ds_read_b128 v[228:231], v143 offset:3072
	s_add_u32 s28, s25, 0x3c00180
	s_addc_u32 s29, s26, 0
	s_add_u32 m0, s98, 0x18000
	global_load_lds_dwordx4 v132, s[28:29]
	s_add_u32 m0, s98, 0x1a000
	global_load_lds_dwordx4 v130, s[28:29]
	s_setprio 1
	s_barrier
	s_waitcnt lgkmcnt(0)
	v_mfma_f32_16x16x32_bf16 v[94:97], v[216:219], v[182:185], v[94:97]
	v_mfma_f32_16x16x32_bf16 v[90:93], v[224:227], v[182:185], v[90:93]
	v_mfma_f32_16x16x32_bf16 v[86:89], v[216:219], v[190:193], v[86:89]
	v_mfma_f32_16x16x32_bf16 v[82:85], v[224:227], v[190:193], v[82:85]
	v_mfma_f32_16x16x32_bf16 v[78:81], v[216:219], v[200:203], v[78:81]
	v_mfma_f32_16x16x32_bf16 v[74:77], v[224:227], v[200:203], v[74:77]
	v_mfma_f32_16x16x32_bf16 v[70:73], v[216:219], v[208:211], v[70:73]
	v_mfma_f32_16x16x32_bf16 v[66:69], v[224:227], v[208:211], v[66:69]
	v_mfma_f32_16x16x32_bf16 v[94:97], v[220:223], v[186:189], v[94:97]
	v_mfma_f32_16x16x32_bf16 v[90:93], v[228:231], v[186:189], v[90:93]
	v_mfma_f32_16x16x32_bf16 v[86:89], v[220:223], v[196:199], v[86:89]
	v_mfma_f32_16x16x32_bf16 v[82:85], v[228:231], v[196:199], v[82:85]
	v_mfma_f32_16x16x32_bf16 v[78:81], v[220:223], v[204:207], v[78:81]
	v_mfma_f32_16x16x32_bf16 v[74:77], v[228:231], v[204:207], v[74:77]
	v_mfma_f32_16x16x32_bf16 v[70:73], v[220:223], v[212:215], v[70:73]
	v_mfma_f32_16x16x32_bf16 v[66:69], v[228:231], v[212:215], v[66:69]
	s_barrier
	s_setprio 0
	ds_read_b128 v[182:185], v141 offset:49152
	ds_read_b128 v[186:189], v141 offset:50176
	ds_read_b128 v[190:193], v139 offset:49152
	ds_read_b128 v[196:199], v139 offset:50176
	ds_read_b128 v[200:203], v137 offset:49152
	ds_read_b128 v[204:207], v137 offset:50176
	ds_read_b128 v[208:211], v135 offset:49152
	ds_read_b128 v[212:215], v135 offset:50176
	s_add_u32 s28, s23, 0x8000180
	s_addc_u32 s29, s24, 0
	s_add_u32 m0, s98, 0x8000
	global_load_lds_dwordx4 v132, s[28:29]
	s_add_u32 m0, s98, 0xa000
	global_load_lds_dwordx4 v130, s[28:29]
	s_setprio 1
	s_barrier
;   #define LDA(dst,b,h) for(int m=0;m<4;++m)for(int k=0;k<2;++k) \
;     dst[m][k]=*reinterpret_cast<const bf16x8*>((char*)SA(b,h)+lds_byte(wr*64+m*16+fr,k*32+fq*8))
;   #define LDB(dst,b,h) for(int n=0;n<2;++n)for(int k=0;k<2;++k) \
;     dst[n][k]=*reinterpret_cast<const bf16x8*>((char*)SB(b,h)+lds_byte(wc*32+n*16+fr,k*32+fq*8))
;   #define MMA(ai,bj,At,Bt_) do{__builtin_amdgcn_s_setprio(1); \
;     for(int m=0;m<4;++m)for(int n=0;n<2;++n)for(int k=0;k<2;++k) \
;       acc[ai][bj][m][n]=__builtin_amdgcn_mfma_f32_16x16x32_bf16(Bt_[n][k],At[m][k],acc[ai][bj][m][n],0,0,0); \
;     __builtin_amdgcn_s_setprio(0);}while(0)
;   #define WAIT_V(n) asm volatile("s_waitcnt vmcnt(" #n ")":::"memory")
;   #define WAIT_L(n) asm volatile("s_waitcnt lgkmcnt(" #n ")":::"memory")
;   #define BAR __builtin_amdgcn_s_barrier()
;   #define SCHED __builtin_amdgcn_sched_barrier(0)
; template <bool TWO, class MID> ...
;     ...
;     BAR; WAIT_L(0); MMA(1,0,At,B0); BAR; SCHED;
;     STAGE_B(SB(1,1),1,t+3);
;     WAIT_V(6); BAR; MMA(1,1,At,B1); BAR;
;   }
;   { LDB(B0,0,0); LDA(At,0,0); STAGE_A(SA(1,1),1,nt-1);
;     BAR; WAIT_L(0); MMA(0,0,At,B0); BAR;
;     LDB(B1,0,1); BAR; WAIT_L(0); MMA(0,1,At,B1); BAR;
;     LDA(At,0,1); WAIT_V(4); BAR; WAIT_L(0); MMA(1,0,At,B0); MMA(1,1,At,B1); BAR; }
	s_waitcnt lgkmcnt(0)
	v_mfma_f32_16x16x32_bf16 v[62:65], v[166:169], v[182:185], v[62:65]
	v_mfma_f32_16x16x32_bf16 v[58:61], v[174:177], v[182:185], v[58:61]
	v_mfma_f32_16x16x32_bf16 v[54:57], v[166:169], v[190:193], v[54:57]
	v_mfma_f32_16x16x32_bf16 v[50:53], v[174:177], v[190:193], v[50:53]
	v_mfma_f32_16x16x32_bf16 v[46:49], v[166:169], v[200:203], v[46:49]
	v_mfma_f32_16x16x32_bf16 v[42:45], v[174:177], v[200:203], v[42:45]
	v_mfma_f32_16x16x32_bf16 v[38:41], v[166:169], v[208:211], v[38:41]
	v_mfma_f32_16x16x32_bf16 v[34:37], v[174:177], v[208:211], v[34:37]
	v_mfma_f32_16x16x32_bf16 v[62:65], v[170:173], v[186:189], v[62:65]
	v_mfma_f32_16x16x32_bf16 v[58:61], v[178:181], v[186:189], v[58:61]
	v_mfma_f32_16x16x32_bf16 v[54:57], v[170:173], v[196:199], v[54:57]
	v_mfma_f32_16x16x32_bf16 v[50:53], v[178:181], v[196:199], v[50:53]
	v_mfma_f32_16x16x32_bf16 v[46:49], v[170:173], v[204:207], v[46:49]
	v_mfma_f32_16x16x32_bf16 v[42:45], v[178:181], v[204:207], v[42:45]
	v_mfma_f32_16x16x32_bf16 v[38:41], v[170:173], v[212:215], v[38:41]
	v_mfma_f32_16x16x32_bf16 v[34:37], v[178:181], v[212:215], v[34:37]
	s_barrier
	s_setprio 0
	s_add_u32 s24, s25, 0x3c80180
	s_addc_u32 s25, s26, 0
	s_add_u32 m0, s98, 0x1c000
	global_load_lds_dwordx4 v132, s[24:25]
	s_add_u32 m0, s98, 0x1e000
	global_load_lds_dwordx4 v130, s[24:25]
	s_waitcnt vmcnt(6)
	s_setprio 1
	s_barrier
	v_mfma_f32_16x16x32_bf16 v[30:33], v[216:219], v[182:185], v[30:33]
	v_mfma_f32_16x16x32_bf16 v[26:29], v[224:227], v[182:185], v[26:29]
	v_mfma_f32_16x16x32_bf16 v[22:25], v[216:219], v[190:193], v[22:25]
	v_mfma_f32_16x16x32_bf16 v[18:21], v[224:227], v[190:193], v[18:21]
	v_mfma_f32_16x16x32_bf16 v[14:17], v[216:219], v[200:203], v[14:17]
	v_mfma_f32_16x16x32_bf16 v[10:13], v[224:227], v[200:203], v[10:13]
	v_mfma_f32_16x16x32_bf16 v[6:9], v[216:219], v[208:211], v[6:9]
	v_mfma_f32_16x16x32_bf16 v[2:5], v[224:227], v[208:211], v[2:5]
	v_mfma_f32_16x16x32_bf16 v[30:33], v[220:223], v[186:189], v[30:33]
	v_mfma_f32_16x16x32_bf16 v[26:29], v[228:231], v[186:189], v[26:29]
	v_mfma_f32_16x16x32_bf16 v[22:25], v[220:223], v[196:199], v[22:25]
	v_mfma_f32_16x16x32_bf16 v[18:21], v[228:231], v[196:199], v[18:21]
	v_mfma_f32_16x16x32_bf16 v[14:17], v[220:223], v[204:207], v[14:17]
	v_mfma_f32_16x16x32_bf16 v[10:13], v[228:231], v[204:207], v[10:13]
	v_mfma_f32_16x16x32_bf16 v[6:9], v[220:223], v[212:215], v[6:9]
	v_mfma_f32_16x16x32_bf16 v[2:5], v[228:231], v[212:215], v[2:5]
	s_setprio 0
	s_add_i32 s22, s22, 2
	s_add_u32 s4, s4, 0x100
	s_addc_u32 s5, s5, 0
	s_cmp_lt_u32 s22, 28
	s_barrier
	s_cbranch_scc1 .LBB0_562
	ds_read_b128 v[152:155], v149
	ds_read_b128 v[156:159], v149 offset:1024
	ds_read_b128 v[160:163], v149 offset:2048
	ds_read_b128 v[164:167], v149 offset:3072
	ds_read_b128 v[168:171], v141
	ds_read_b128 v[172:175], v141 offset:1024
	ds_read_b128 v[176:179], v139
	ds_read_b128 v[180:183], v139 offset:1024
	ds_read_b128 v[184:187], v137
	ds_read_b128 v[188:191], v137 offset:1024
	ds_read_b128 v[196:199], v135
	ds_read_b128 v[200:203], v135 offset:1024
	s_add_u32 s4, s19, 0x80f80
	s_addc_u32 s5, s21, 0
	v_lshl_add_u64 v[132:133], s[4:5], 0, v[132:133]
	v_readfirstlane_b32 s12, v148
	s_mov_b32 m0, s12
	global_load_lds_dwordx4 v[132:133], off
	v_lshl_add_u64 v[130:131], s[4:5], 0, v[130:131]
	v_readfirstlane_b32 s4, v150
	s_mov_b32 m0, s4
	global_load_lds_dwordx4 v[130:131], off
	s_setprio 1
	s_barrier
	s_waitcnt lgkmcnt(0)
	v_mfma_f32_16x16x32_bf16 v[126:129], v[152:155], v[168:171], v[126:129]
	v_mfma_f32_16x16x32_bf16 v[122:125], v[160:163], v[168:171], v[122:125]
	v_mfma_f32_16x16x32_bf16 v[114:117], v[160:163], v[176:179], v[114:117]
	v_mfma_f32_16x16x32_bf16 v[106:109], v[160:163], v[184:187], v[106:109]
	v_mfma_f32_16x16x32_bf16 v[98:101], v[160:163], v[196:199], v[98:101]
	v_mfma_f32_16x16x32_bf16 v[126:129], v[156:159], v[172:175], v[126:129]
	v_mfma_f32_16x16x32_bf16 v[122:125], v[164:167], v[172:175], v[122:125]
	v_mfma_f32_16x16x32_bf16 v[118:121], v[152:155], v[176:179], v[118:121]
	v_mfma_f32_16x16x32_bf16 v[114:117], v[164:167], v[180:183], v[114:117]
	v_mfma_f32_16x16x32_bf16 v[110:113], v[152:155], v[184:187], v[110:113]
	v_mfma_f32_16x16x32_bf16 v[106:109], v[164:167], v[188:191], v[106:109]
	v_mfma_f32_16x16x32_bf16 v[102:105], v[152:155], v[196:199], v[102:105]
	v_mfma_f32_16x16x32_bf16 v[98:101], v[164:167], v[200:203], v[98:101]
	v_mfma_f32_16x16x32_bf16 v[130:133], v[156:159], v[180:183], v[118:121]
	v_mfma_f32_16x16x32_bf16 v[148:151], v[156:159], v[188:191], v[110:113]
	v_mfma_f32_16x16x32_bf16 v[204:207], v[156:159], v[200:203], v[102:105]
	s_barrier
	s_setprio 0
	s_nop 0
	ds_read_b128 v[102:105], v147
	ds_read_b128 v[110:113], v147 offset:1024
	ds_read_b128 v[118:121], v147 offset:2048
	ds_read_b128 v[208:211], v147 offset:3072
	s_setprio 1
	s_barrier
	s_waitcnt lgkmcnt(0)
	v_mfma_f32_16x16x32_bf16 v[90:93], v[118:121], v[168:171], v[90:93]
	v_mfma_f32_16x16x32_bf16 v[82:85], v[118:121], v[176:179], v[82:85]
	v_mfma_f32_16x16x32_bf16 v[74:77], v[118:121], v[184:187], v[74:77]
	v_mfma_f32_16x16x32_bf16 v[66:69], v[118:121], v[196:199], v[66:69]
	v_mfma_f32_16x16x32_bf16 v[94:97], v[102:105], v[168:171], v[94:97]
	v_mfma_f32_16x16x32_bf16 v[90:93], v[208:211], v[172:175], v[90:93]
	v_mfma_f32_16x16x32_bf16 v[86:89], v[102:105], v[176:179], v[86:89]
	v_mfma_f32_16x16x32_bf16 v[82:85], v[208:211], v[180:183], v[82:85]
	v_mfma_f32_16x16x32_bf16 v[78:81], v[102:105], v[184:187], v[78:81]
	v_mfma_f32_16x16x32_bf16 v[74:77], v[208:211], v[188:191], v[74:77]
	v_mfma_f32_16x16x32_bf16 v[70:73], v[102:105], v[196:199], v[70:73]
	v_mfma_f32_16x16x32_bf16 v[66:69], v[208:211], v[200:203], v[66:69]
	v_mfma_f32_16x16x32_bf16 v[212:215], v[110:113], v[172:175], v[94:97]
	v_mfma_f32_16x16x32_bf16 v[168:171], v[110:113], v[180:183], v[86:89]
	v_mfma_f32_16x16x32_bf16 v[172:175], v[110:113], v[188:191], v[78:81]
	v_mfma_f32_16x16x32_bf16 v[176:179], v[110:113], v[200:203], v[70:73]
	s_barrier
;   #define LDA(dst,b,h) for(int m=0;m<4;++m)for(int k=0;k<2;++k) \
;     dst[m][k]=*reinterpret_cast<const bf16x8*>((char*)SA(b,h)+lds_byte(wr*64+m*16+fr,k*32+fq*8))
;   #define LDB(dst,b,h) for(int n=0;n<2;++n)for(int k=0;k<2;++k) \
;     dst[n][k]=*reinterpret_cast<const bf16x8*>((char*)SB(b,h)+lds_byte(wc*32+n*16+fr,k*32+fq*8))
;   #define MMA(ai,bj,At,Bt_) do{__builtin_amdgcn_s_setprio(1); \
;     for(int m=0;m<4;++m)for(int n=0;n<2;++n)for(int k=0;k<2;++k) \
;       acc[ai][bj][m][n]=__builtin_amdgcn_mfma_f32_16x16x32_bf16(Bt_[n][k],At[m][k],acc[ai][bj][m][n],0,0,0); \
;     __builtin_amdgcn_s_setprio(0);}while(0)
;   #define WAIT_V(n) asm volatile("s_waitcnt vmcnt(" #n ")":::"memory")
;   #define WAIT_L(n) asm volatile("s_waitcnt lgkmcnt(" #n ")":::"memory")
;   #define BAR __builtin_amdgcn_s_barrier()
; template <bool TWO, class MID> ...
;     ...
;     LDA(At,0,1); WAIT_V(4); BAR; WAIT_L(0); MMA(1,0,At,B0); MMA(1,1,At,B1); BAR; }
;   { LDB(B0,1,0); LDA(At,1,0); WAIT_V(2); BAR; WAIT_L(0); MMA(0,0,At,B0); BAR;
	s_setprio 0
	s_nop 0
	ds_read_b128 v[70:73], v141 offset:16384
	ds_read_b128 v[78:81], v141 offset:17408
	ds_read_b128 v[86:89], v139 offset:16384
	ds_read_b128 v[94:97], v139 offset:17408
	ds_read_b128 v[180:183], v137 offset:16384
	ds_read_b128 v[184:187], v137 offset:17408
	ds_read_b128 v[188:191], v135 offset:16384
	ds_read_b128 v[196:199], v135 offset:17408
	s_waitcnt vmcnt(4)
	s_setprio 1
	s_barrier
	s_waitcnt lgkmcnt(0)
	v_mfma_f32_16x16x32_bf16 v[62:65], v[152:155], v[70:73], v[62:65]
	v_mfma_f32_16x16x32_bf16 v[58:61], v[160:163], v[70:73], v[58:61]
	v_mfma_f32_16x16x32_bf16 v[54:57], v[152:155], v[86:89], v[54:57]
	v_mfma_f32_16x16x32_bf16 v[50:53], v[160:163], v[86:89], v[50:53]
	v_mfma_f32_16x16x32_bf16 v[38:41], v[152:155], v[188:191], v[38:41]
	v_mfma_f32_16x16x32_bf16 v[34:37], v[160:163], v[188:191], v[34:37]
	v_mfma_f32_16x16x32_bf16 v[62:65], v[156:159], v[78:81], v[62:65]
	v_mfma_f32_16x16x32_bf16 v[58:61], v[164:167], v[78:81], v[58:61]
	v_mfma_f32_16x16x32_bf16 v[54:57], v[156:159], v[94:97], v[54:57]
	v_mfma_f32_16x16x32_bf16 v[50:53], v[164:167], v[94:97], v[50:53]
	v_mfma_f32_16x16x32_bf16 v[46:49], v[152:155], v[180:183], v[46:49]
	v_mfma_f32_16x16x32_bf16 v[42:45], v[160:163], v[180:183], v[42:45]
	v_mfma_f32_16x16x32_bf16 v[38:41], v[156:159], v[196:199], v[38:41]
	v_mfma_f32_16x16x32_bf16 v[34:37], v[164:167], v[196:199], v[34:37]
	v_mfma_f32_16x16x32_bf16 v[200:203], v[156:159], v[184:187], v[46:49]
	v_mfma_f32_16x16x32_bf16 v[216:219], v[164:167], v[184:187], v[42:45]
	s_setprio 0
	s_setprio 1
	v_mfma_f32_16x16x32_bf16 v[22:25], v[102:105], v[86:89], v[22:25]
	v_mfma_f32_16x16x32_bf16 v[18:21], v[118:121], v[86:89], v[18:21]
	v_mfma_f32_16x16x32_bf16 v[6:9], v[102:105], v[188:191], v[6:9]
	v_mfma_f32_16x16x32_bf16 v[2:5], v[118:121], v[188:191], v[2:5]
	v_mfma_f32_16x16x32_bf16 v[30:33], v[102:105], v[70:73], v[30:33]
	v_mfma_f32_16x16x32_bf16 v[26:29], v[118:121], v[70:73], v[26:29]
	v_mfma_f32_16x16x32_bf16 v[22:25], v[110:113], v[94:97], v[22:25]
	v_mfma_f32_16x16x32_bf16 v[18:21], v[208:211], v[94:97], v[18:21]
	v_mfma_f32_16x16x32_bf16 v[14:17], v[102:105], v[180:183], v[14:17]
	v_mfma_f32_16x16x32_bf16 v[10:13], v[118:121], v[180:183], v[10:13]
	v_mfma_f32_16x16x32_bf16 v[6:9], v[110:113], v[196:199], v[6:9]
	v_mfma_f32_16x16x32_bf16 v[2:5], v[208:211], v[196:199], v[2:5]
	v_mfma_f32_16x16x32_bf16 v[152:155], v[110:113], v[78:81], v[30:33]
	v_mfma_f32_16x16x32_bf16 v[156:159], v[208:211], v[78:81], v[26:29]
	v_mfma_f32_16x16x32_bf16 v[160:163], v[110:113], v[184:187], v[14:17]
	v_mfma_f32_16x16x32_bf16 v[164:167], v[208:211], v[184:187], v[10:13]
	s_barrier
	s_setprio 0
	s_nop 0
	ds_read_b128 v[10:13], v145
	ds_read_b128 v[14:17], v145 offset:1024
	ds_read_b128 v[180:183], v145 offset:2048
	ds_read_b128 v[144:147], v145 offset:3072
	ds_read_b128 v[26:29], v141 offset:32768
	ds_read_b128 v[30:33], v141 offset:33792
	ds_read_b128 v[42:45], v139 offset:32768
	ds_read_b128 v[46:49], v139 offset:33792
	ds_read_b128 v[184:187], v137 offset:32768
	ds_read_b128 v[188:191], v137 offset:33792
	ds_read_b128 v[196:199], v135 offset:32768
	ds_read_b128 v[208:211], v135 offset:33792
	s_waitcnt vmcnt(2)
	s_setprio 1
	s_barrier
	s_waitcnt lgkmcnt(0)
	v_mfma_f32_16x16x32_bf16 v[70:73], v[10:13], v[26:29], v[126:129]
	v_mfma_f32_16x16x32_bf16 v[126:129], v[14:17], v[30:33], v[70:73]
	v_mfma_f32_16x16x32_bf16 v[70:73], v[180:183], v[26:29], v[122:125]
	v_mfma_f32_16x16x32_bf16 v[118:121], v[144:147], v[30:33], v[70:73]
	v_mfma_f32_16x16x32_bf16 v[70:73], v[10:13], v[42:45], v[130:133]
	v_mfma_f32_16x16x32_bf16 v[110:113], v[14:17], v[46:49], v[70:73]
	v_mfma_f32_16x16x32_bf16 v[70:73], v[180:183], v[42:45], v[114:117]
	v_mfma_f32_16x16x32_bf16 v[102:105], v[144:147], v[46:49], v[70:73]
	v_mfma_f32_16x16x32_bf16 v[70:73], v[10:13], v[184:187], v[148:151]
	v_mfma_f32_16x16x32_bf16 v[94:97], v[14:17], v[188:191], v[70:73]
	v_mfma_f32_16x16x32_bf16 v[70:73], v[180:183], v[184:187], v[106:109]
	v_mfma_f32_16x16x32_bf16 v[86:89], v[144:147], v[188:191], v[70:73]
	v_mfma_f32_16x16x32_bf16 v[70:73], v[10:13], v[196:199], v[204:207]
	v_mfma_f32_16x16x32_bf16 v[78:81], v[14:17], v[208:211], v[70:73]
	v_mfma_f32_16x16x32_bf16 v[70:73], v[180:183], v[196:199], v[98:101]
	v_mfma_f32_16x16x32_bf16 v[70:73], v[144:147], v[208:211], v[70:73]
	s_barrier
;   #define LDA(dst,b,h) for(int m=0;m<4;++m)for(int k=0;k<2;++k) \
;     dst[m][k]=*reinterpret_cast<const bf16x8*>((char*)SA(b,h)+lds_byte(wr*64+m*16+fr,k*32+fq*8))
;   #define LDB(dst,b,h) for(int n=0;n<2;++n)for(int k=0;k<2;++k) \
;     dst[n][k]=*reinterpret_cast<const bf16x8*>((char*)SB(b,h)+lds_byte(wc*32+n*16+fr,k*32+fq*8))
;   #define MMA(ai,bj,At,Bt_) do{__builtin_amdgcn_s_setprio(1); \
;     for(int m=0;m<4;++m)for(int n=0;n<2;++n)for(int k=0;k<2;++k) \
;       acc[ai][bj][m][n]=__builtin_amdgcn_mfma_f32_16x16x32_bf16(Bt_[n][k],At[m][k],acc[ai][bj][m][n],0,0,0); \
;     __builtin_amdgcn_s_setprio(0);}while(0)
;   #define WAIT_V(n) asm volatile("s_waitcnt vmcnt(" #n ")":::"memory")
;   #define WAIT_L(n) asm volatile("s_waitcnt lgkmcnt(" #n ")":::"memory")
;   #define BAR __builtin_amdgcn_s_barrier()
; template <bool TWO, class MID> ...
;     ...
;     LDB(B1,1,1); WAIT_V(0); BAR; WAIT_L(0); MMA(0,1,At,B1); BAR;
;     LDA(At,1,1); BAR; WAIT_L(0); MMA(1,0,At,B0); MMA(1,1,At,B1); BAR; }
;   if(wr==0)BAR;
	s_setprio 0
	ds_read_b128 v[130:133], v143
	ds_read_b128 v[148:151], v143 offset:1024
	ds_read_b128 v[204:207], v143 offset:2048
	ds_read_b128 v[220:223], v143 offset:3072
	s_waitcnt vmcnt(0)
	s_setprio 1
	s_barrier
	s_waitcnt lgkmcnt(0)
	v_mfma_f32_16x16x32_bf16 v[98:101], v[130:133], v[26:29], v[212:215]
	v_mfma_f32_16x16x32_bf16 v[26:29], v[204:207], v[26:29], v[90:93]
	v_mfma_f32_16x16x32_bf16 v[114:117], v[220:223], v[30:33], v[26:29]
	v_mfma_f32_16x16x32_bf16 v[26:29], v[130:133], v[42:45], v[168:171]
	v_mfma_f32_16x16x32_bf16 v[106:109], v[148:151], v[46:49], v[26:29]
	v_mfma_f32_16x16x32_bf16 v[26:29], v[204:207], v[42:45], v[82:85]
	v_mfma_f32_16x16x32_bf16 v[122:125], v[148:151], v[30:33], v[98:101]
	v_mfma_f32_16x16x32_bf16 v[98:101], v[220:223], v[46:49], v[26:29]
	v_mfma_f32_16x16x32_bf16 v[26:29], v[130:133], v[184:187], v[172:175]
	v_mfma_f32_16x16x32_bf16 v[90:93], v[148:151], v[188:191], v[26:29]
	v_mfma_f32_16x16x32_bf16 v[26:29], v[204:207], v[184:187], v[74:77]
	v_mfma_f32_16x16x32_bf16 v[82:85], v[220:223], v[188:191], v[26:29]
	v_mfma_f32_16x16x32_bf16 v[26:29], v[130:133], v[196:199], v[176:179]
	v_mfma_f32_16x16x32_bf16 v[74:77], v[148:151], v[208:211], v[26:29]
	v_mfma_f32_16x16x32_bf16 v[26:29], v[204:207], v[196:199], v[66:69]
	v_mfma_f32_16x16x32_bf16 v[66:69], v[220:223], v[208:211], v[26:29]
	s_barrier
	s_setprio 0
	ds_read_b128 v[168:171], v141 offset:49152
	ds_read_b128 v[140:143], v141 offset:50176
	ds_read_b128 v[172:175], v139 offset:49152
	ds_read_b128 v[176:179], v139 offset:50176
	ds_read_b128 v[184:187], v137 offset:49152
	ds_read_b128 v[136:139], v137 offset:50176
	ds_read_b128 v[188:191], v135 offset:49152
	ds_read_b128 v[196:199], v135 offset:50176
	s_setprio 1
	s_barrier
	s_waitcnt lgkmcnt(0)
	v_mfma_f32_16x16x32_bf16 v[26:29], v[10:13], v[168:171], v[62:65]
	v_mfma_f32_16x16x32_bf16 v[62:65], v[14:17], v[140:143], v[26:29]
	v_mfma_f32_16x16x32_bf16 v[26:29], v[180:183], v[168:171], v[58:61]
	v_mfma_f32_16x16x32_bf16 v[58:61], v[144:147], v[140:143], v[26:29]
	v_mfma_f32_16x16x32_bf16 v[26:29], v[10:13], v[172:175], v[54:57]
	v_mfma_f32_16x16x32_bf16 v[46:49], v[14:17], v[176:179], v[26:29]
	v_mfma_f32_16x16x32_bf16 v[26:29], v[180:183], v[172:175], v[50:53]
	v_mfma_f32_16x16x32_bf16 v[42:45], v[144:147], v[176:179], v[26:29]
	v_mfma_f32_16x16x32_bf16 v[26:29], v[10:13], v[184:187], v[200:203]
	v_mfma_f32_16x16x32_bf16 v[10:13], v[10:13], v[188:191], v[38:41]
	v_mfma_f32_16x16x32_bf16 v[30:33], v[14:17], v[136:139], v[26:29]
	v_mfma_f32_16x16x32_bf16 v[26:29], v[180:183], v[184:187], v[216:219]
	v_mfma_f32_16x16x32_bf16 v[14:17], v[14:17], v[196:199], v[10:13]
	v_mfma_f32_16x16x32_bf16 v[10:13], v[180:183], v[188:191], v[34:37]
	v_mfma_f32_16x16x32_bf16 v[26:29], v[144:147], v[136:139], v[26:29]
	v_mfma_f32_16x16x32_bf16 v[10:13], v[144:147], v[196:199], v[10:13]
	s_setprio 0
	s_setprio 1
	v_mfma_f32_16x16x32_bf16 v[34:37], v[130:133], v[168:171], v[152:155]
	v_mfma_f32_16x16x32_bf16 v[54:57], v[148:151], v[140:143], v[34:37]
	v_mfma_f32_16x16x32_bf16 v[34:37], v[204:207], v[168:171], v[156:159]
	v_mfma_f32_16x16x32_bf16 v[18:21], v[204:207], v[172:175], v[18:21]
	v_mfma_f32_16x16x32_bf16 v[50:53], v[220:223], v[140:143], v[34:37]
	v_mfma_f32_16x16x32_bf16 v[22:25], v[130:133], v[172:175], v[22:25]
	v_mfma_f32_16x16x32_bf16 v[34:37], v[220:223], v[176:179], v[18:21]
	v_mfma_f32_16x16x32_bf16 v[18:21], v[130:133], v[184:187], v[160:163]
	v_mfma_f32_16x16x32_bf16 v[38:41], v[148:151], v[176:179], v[22:25]
	v_mfma_f32_16x16x32_bf16 v[22:25], v[148:151], v[136:139], v[18:21]
	v_mfma_f32_16x16x32_bf16 v[18:21], v[204:207], v[184:187], v[164:167]
	v_mfma_f32_16x16x32_bf16 v[6:9], v[130:133], v[188:191], v[6:9]
	v_mfma_f32_16x16x32_bf16 v[2:5], v[204:207], v[188:191], v[2:5]
	v_mfma_f32_16x16x32_bf16 v[18:21], v[220:223], v[136:139], v[18:21]
	v_mfma_f32_16x16x32_bf16 v[6:9], v[148:151], v[196:199], v[6:9]
	v_mfma_f32_16x16x32_bf16 v[2:5], v[220:223], v[196:199], v[2:5]
	s_setprio 0
	v_cmp_gt_u32_e32 vcc, s30, v1
	s_barrier
	s_and_saveexec_b64 s[4:5], vcc
	s_cbranch_execz .LBB0_565
	s_barrier

;   #define LDA(dst,b,h) for(int m=0;m<4;++m)for(int k=0;k<2;++k) \
;     dst[m][k]=*reinterpret_cast<const bf16x8*>((char*)SA(b,h)+lds_byte(wr*64+m*16+fr,k*32+fq*8))
;   #define LDB(dst,b,h) for(int n=0;n<2;++n)for(int k=0;k<2;++k) \
;     dst[n][k]=*reinterpret_cast<const bf16x8*>((char*)SB(b,h)+lds_byte(wc*32+n*16+fr,k*32+fq*8))
;   #define MMA(ai,bj,At,Bt_) do{__builtin_amdgcn_s_setprio(1); \
;     for(int m=0;m<4;++m)for(int n=0;n<2;++n)for(int k=0;k<2;++k) \
;       acc[ai][bj][m][n]=__builtin_amdgcn_mfma_f32_16x16x32_bf16(Bt_[n][k],At[m][k],acc[ai][bj][m][n],0,0,0); \
;     __builtin_amdgcn_s_setprio(0);}while(0)
;   #define WAIT_V(n) asm volatile("s_waitcnt vmcnt(" #n ")":::"memory")
;   #define WAIT_L(n) asm volatile("s_waitcnt lgkmcnt(" #n ")":::"memory")
;   #define BAR __builtin_amdgcn_s_barrier()
;   #define SCHED __builtin_amdgcn_sched_barrier(0)
; template <bool TWO, class MID> ...
;     ...
;   for(int t=0;t<nt-2;t+=2){
;     if (TWO && t == nt1) mid();
;     LDB(B0,0,0); SCHED; LDA(At,0,0); STAGE_A(SA(1,1),1,t+1);
;     WAIT_L(8); BAR; WAIT_L(0); MMA(0,0,At,B0); BAR; SCHED;
;     LDB(B1,0,1); STAGE_B(SB(0,0),0,t+2);
;     BAR; WAIT_L(0); MMA(0,1,At,B1); BAR;
;     LDA(At,0,1); STAGE_A(SA(0,0),0,t+2);
;     BAR; WAIT_L(0); MMA(1,0,At,B0); BAR; SCHED;
;     STAGE_B(SB(0,1),1,t+2);
;     WAIT_V(6); BAR; MMA(1,1,At,B1); BAR;
.LBB0_620:
	ds_read_b128 v[166:169], v149
	ds_read_b128 v[170:173], v149 offset:1024
	ds_read_b128 v[174:177], v149 offset:2048
	ds_read_b128 v[178:181], v149 offset:3072
	ds_read_b128 v[182:185], v141
	ds_read_b128 v[186:189], v141 offset:1024
	ds_read_b128 v[190:193], v139
	ds_read_b128 v[196:199], v139 offset:1024
	ds_read_b128 v[200:203], v137
	ds_read_b128 v[204:207], v137 offset:1024
	ds_read_b128 v[208:211], v135
	ds_read_b128 v[212:215], v135 offset:1024
	s_add_u32 s15, s0, s16
	s_addc_u32 s18, s1, s17
	s_add_u32 s24, s15, 0x10200080
	s_addc_u32 s25, s18, 0
	s_add_u32 m0, s98, 0xc000
	global_load_lds_dwordx4 v132, s[24:25]
	s_add_u32 m0, s98, 0xe000
	global_load_lds_dwordx4 v130, s[24:25]
	s_waitcnt lgkmcnt(8)
	s_setprio 1
	s_barrier
	s_waitcnt lgkmcnt(0)
	v_mfma_f32_16x16x32_bf16 v[126:129], v[166:169], v[182:185], v[126:129]
	v_mfma_f32_16x16x32_bf16 v[122:125], v[174:177], v[182:185], v[122:125]
	v_mfma_f32_16x16x32_bf16 v[118:121], v[166:169], v[190:193], v[118:121]
	v_mfma_f32_16x16x32_bf16 v[114:117], v[174:177], v[190:193], v[114:117]
	v_mfma_f32_16x16x32_bf16 v[110:113], v[166:169], v[200:203], v[110:113]
	v_mfma_f32_16x16x32_bf16 v[106:109], v[174:177], v[200:203], v[106:109]
	v_mfma_f32_16x16x32_bf16 v[102:105], v[166:169], v[208:211], v[102:105]
	v_mfma_f32_16x16x32_bf16 v[98:101], v[174:177], v[208:211], v[98:101]
	v_mfma_f32_16x16x32_bf16 v[126:129], v[170:173], v[186:189], v[126:129]
	v_mfma_f32_16x16x32_bf16 v[122:125], v[178:181], v[186:189], v[122:125]
	v_mfma_f32_16x16x32_bf16 v[118:121], v[170:173], v[196:199], v[118:121]
	v_mfma_f32_16x16x32_bf16 v[114:117], v[178:181], v[196:199], v[114:117]
	v_mfma_f32_16x16x32_bf16 v[110:113], v[170:173], v[204:207], v[110:113]
	v_mfma_f32_16x16x32_bf16 v[106:109], v[178:181], v[204:207], v[106:109]
	v_mfma_f32_16x16x32_bf16 v[102:105], v[170:173], v[212:215], v[102:105]
	v_mfma_f32_16x16x32_bf16 v[98:101], v[178:181], v[212:215], v[98:101]
	s_barrier
	s_setprio 0
	s_add_u32 s19, s0, s4
	ds_read_b128 v[216:219], v147
	ds_read_b128 v[220:223], v147 offset:1024
	ds_read_b128 v[224:227], v147 offset:2048
	ds_read_b128 v[228:231], v147 offset:3072
	s_addc_u32 s24, s1, s5
	s_add_u32 s26, s19, 0x5c00100
	s_addc_u32 s27, s24, 0
	s_add_u32 m0, s98, 0x10000
	global_load_lds_dwordx4 v132, s[26:27]
	s_add_u32 m0, s98, 0x12000
	global_load_lds_dwordx4 v130, s[26:27]
	s_setprio 1
	s_barrier
	s_waitcnt lgkmcnt(0)
	v_mfma_f32_16x16x32_bf16 v[94:97], v[216:219], v[182:185], v[94:97]
	v_mfma_f32_16x16x32_bf16 v[90:93], v[224:227], v[182:185], v[90:93]
	v_mfma_f32_16x16x32_bf16 v[86:89], v[216:219], v[190:193], v[86:89]
	v_mfma_f32_16x16x32_bf16 v[82:85], v[224:227], v[190:193], v[82:85]
	v_mfma_f32_16x16x32_bf16 v[78:81], v[216:219], v[200:203], v[78:81]
	v_mfma_f32_16x16x32_bf16 v[74:77], v[224:227], v[200:203], v[74:77]
	v_mfma_f32_16x16x32_bf16 v[70:73], v[216:219], v[208:211], v[70:73]
	v_mfma_f32_16x16x32_bf16 v[66:69], v[224:227], v[208:211], v[66:69]
	v_mfma_f32_16x16x32_bf16 v[94:97], v[220:223], v[186:189], v[94:97]
	v_mfma_f32_16x16x32_bf16 v[90:93], v[228:231], v[186:189], v[90:93]
	v_mfma_f32_16x16x32_bf16 v[86:89], v[220:223], v[196:199], v[86:89]
	v_mfma_f32_16x16x32_bf16 v[82:85], v[228:231], v[196:199], v[82:85]
	v_mfma_f32_16x16x32_bf16 v[78:81], v[220:223], v[204:207], v[78:81]
	v_mfma_f32_16x16x32_bf16 v[74:77], v[228:231], v[204:207], v[74:77]
	v_mfma_f32_16x16x32_bf16 v[70:73], v[220:223], v[212:215], v[70:73]
	v_mfma_f32_16x16x32_bf16 v[66:69], v[228:231], v[212:215], v[66:69]
	s_barrier
	s_setprio 0
	ds_read_b128 v[182:185], v141 offset:16384
	ds_read_b128 v[186:189], v141 offset:17408
	ds_read_b128 v[190:193], v139 offset:16384
	ds_read_b128 v[196:199], v139 offset:17408
	ds_read_b128 v[200:203], v137 offset:16384
	ds_read_b128 v[204:207], v137 offset:17408
	ds_read_b128 v[208:211], v135 offset:16384
	ds_read_b128 v[212:215], v135 offset:17408
	s_add_u32 s26, s15, 0x10000100
	s_addc_u32 s27, s18, 0
	s_add_u32 m0, s98, 0x0
	global_load_lds_dwordx4 v132, s[26:27]
	s_add_u32 m0, s98, 0x2000
	global_load_lds_dwordx4 v130, s[26:27]
	s_setprio 1
	s_barrier
	s_waitcnt lgkmcnt(0)
	v_mfma_f32_16x16x32_bf16 v[62:65], v[166:169], v[182:185], v[62:65]
	v_mfma_f32_16x16x32_bf16 v[58:61], v[174:177], v[182:185], v[58:61]
	v_mfma_f32_16x16x32_bf16 v[54:57], v[166:169], v[190:193], v[54:57]
	v_mfma_f32_16x16x32_bf16 v[50:53], v[174:177], v[190:193], v[50:53]
	v_mfma_f32_16x16x32_bf16 v[46:49], v[166:169], v[200:203], v[46:49]
	v_mfma_f32_16x16x32_bf16 v[42:45], v[174:177], v[200:203], v[42:45]
	v_mfma_f32_16x16x32_bf16 v[38:41], v[166:169], v[208:211], v[38:41]
	v_mfma_f32_16x16x32_bf16 v[34:37], v[174:177], v[208:211], v[34:37]
	v_mfma_f32_16x16x32_bf16 v[62:65], v[170:173], v[186:189], v[62:65]
	v_mfma_f32_16x16x32_bf16 v[58:61], v[178:181], v[186:189], v[58:61]
	v_mfma_f32_16x16x32_bf16 v[54:57], v[170:173], v[196:199], v[54:57]
	v_mfma_f32_16x16x32_bf16 v[50:53], v[178:181], v[196:199], v[50:53]
	v_mfma_f32_16x16x32_bf16 v[46:49], v[170:173], v[204:207], v[46:49]
	v_mfma_f32_16x16x32_bf16 v[42:45], v[178:181], v[204:207], v[42:45]
	v_mfma_f32_16x16x32_bf16 v[38:41], v[170:173], v[212:215], v[38:41]
	v_mfma_f32_16x16x32_bf16 v[34:37], v[178:181], v[212:215], v[34:37]
	s_barrier
	s_setprio 0
	s_add_u32 s26, s19, 0x5e00100
	s_addc_u32 s27, s24, 0
	s_add_u32 m0, s98, 0x14000
	global_load_lds_dwordx4 v132, s[26:27]
	s_add_u32 m0, s98, 0x16000
	global_load_lds_dwordx4 v130, s[26:27]
	s_waitcnt vmcnt(6)
	s_setprio 1
	s_barrier
;   #define LDA(dst,b,h) for(int m=0;m<4;++m)for(int k=0;k<2;++k) \
;     dst[m][k]=*reinterpret_cast<const bf16x8*>((char*)SA(b,h)+lds_byte(wr*64+m*16+fr,k*32+fq*8))
;   #define LDB(dst,b,h) for(int n=0;n<2;++n)for(int k=0;k<2;++k) \
;     dst[n][k]=*reinterpret_cast<const bf16x8*>((char*)SB(b,h)+lds_byte(wc*32+n*16+fr,k*32+fq*8))
;   #define MMA(ai,bj,At,Bt_) do{__builtin_amdgcn_s_setprio(1); \
;     for(int m=0;m<4;++m)for(int n=0;n<2;++n)for(int k=0;k<2;++k) \
;       acc[ai][bj][m][n]=__builtin_amdgcn_mfma_f32_16x16x32_bf16(Bt_[n][k],At[m][k],acc[ai][bj][m][n],0,0,0); \
;     __builtin_amdgcn_s_setprio(0);}while(0)
;   #define WAIT_V(n) asm volatile("s_waitcnt vmcnt(" #n ")":::"memory")
;   #define WAIT_L(n) asm volatile("s_waitcnt lgkmcnt(" #n ")":::"memory")
;   #define BAR __builtin_amdgcn_s_barrier()
;   #define SCHED __builtin_amdgcn_sched_barrier(0)
; template <bool TWO, class MID> ...
;     ...
;     WAIT_V(6); BAR; MMA(1,1,At,B1); BAR;
;     LDB(B0,1,0); SCHED; LDA(At,1,0); STAGE_A(SA(0,1),1,t+2);
;     WAIT_L(8); BAR; WAIT_L(0); MMA(0,0,At,B0); BAR; SCHED;
;     LDB(B1,1,1); STAGE_B(SB(1,0),0,t+3);
;     BAR; WAIT_L(0); MMA(0,1,At,B1); BAR;
;     LDA(At,1,1); STAGE_A(SA(1,0),0,t+3);
;     BAR; WAIT_L(0); MMA(1,0,At,B0); BAR; SCHED;
	v_mfma_f32_16x16x32_bf16 v[30:33], v[216:219], v[182:185], v[30:33]
	v_mfma_f32_16x16x32_bf16 v[26:29], v[224:227], v[182:185], v[26:29]
	ds_read_b128 v[166:169], v145
	v_mfma_f32_16x16x32_bf16 v[22:25], v[216:219], v[190:193], v[22:25]
	v_mfma_f32_16x16x32_bf16 v[18:21], v[224:227], v[190:193], v[18:21]
	ds_read_b128 v[170:173], v145 offset:1024
	v_mfma_f32_16x16x32_bf16 v[14:17], v[216:219], v[200:203], v[14:17]
	v_mfma_f32_16x16x32_bf16 v[10:13], v[224:227], v[200:203], v[10:13]
	ds_read_b128 v[174:177], v145 offset:2048
	v_mfma_f32_16x16x32_bf16 v[6:9], v[216:219], v[208:211], v[6:9]
	v_mfma_f32_16x16x32_bf16 v[2:5], v[224:227], v[208:211], v[2:5]
	ds_read_b128 v[178:181], v145 offset:3072
	v_mfma_f32_16x16x32_bf16 v[30:33], v[220:223], v[186:189], v[30:33]
	v_mfma_f32_16x16x32_bf16 v[26:29], v[228:231], v[186:189], v[26:29]
	v_mfma_f32_16x16x32_bf16 v[22:25], v[220:223], v[196:199], v[22:25]
	v_mfma_f32_16x16x32_bf16 v[18:21], v[228:231], v[196:199], v[18:21]
	v_mfma_f32_16x16x32_bf16 v[14:17], v[220:223], v[204:207], v[14:17]
	v_mfma_f32_16x16x32_bf16 v[10:13], v[228:231], v[204:207], v[10:13]
	v_mfma_f32_16x16x32_bf16 v[6:9], v[220:223], v[212:215], v[6:9]
	v_mfma_f32_16x16x32_bf16 v[2:5], v[228:231], v[212:215], v[2:5]
	s_barrier
	s_setprio 0
	ds_read_b128 v[182:185], v141 offset:32768
	ds_read_b128 v[186:189], v141 offset:33792
	ds_read_b128 v[190:193], v139 offset:32768
	ds_read_b128 v[196:199], v139 offset:33792
	ds_read_b128 v[200:203], v137 offset:32768
	ds_read_b128 v[204:207], v137 offset:33792
	ds_read_b128 v[208:211], v135 offset:32768
	ds_read_b128 v[212:215], v135 offset:33792
	s_add_u32 s26, s15, 0x10200100
	s_addc_u32 s27, s18, 0
	s_add_u32 m0, s98, 0x4000
	global_load_lds_dwordx4 v132, s[26:27]
	s_add_u32 m0, s98, 0x6000
	global_load_lds_dwordx4 v130, s[26:27]
	s_waitcnt lgkmcnt(8)
	s_setprio 1
	s_barrier
	s_waitcnt lgkmcnt(0)
	v_mfma_f32_16x16x32_bf16 v[126:129], v[166:169], v[182:185], v[126:129]
	v_mfma_f32_16x16x32_bf16 v[122:125], v[174:177], v[182:185], v[122:125]
	v_mfma_f32_16x16x32_bf16 v[118:121], v[166:169], v[190:193], v[118:121]
	v_mfma_f32_16x16x32_bf16 v[114:117], v[174:177], v[190:193], v[114:117]
	v_mfma_f32_16x16x32_bf16 v[110:113], v[166:169], v[200:203], v[110:113]
	v_mfma_f32_16x16x32_bf16 v[106:109], v[174:177], v[200:203], v[106:109]
	v_mfma_f32_16x16x32_bf16 v[102:105], v[166:169], v[208:211], v[102:105]
	v_mfma_f32_16x16x32_bf16 v[98:101], v[174:177], v[208:211], v[98:101]
	v_mfma_f32_16x16x32_bf16 v[126:129], v[170:173], v[186:189], v[126:129]
	v_mfma_f32_16x16x32_bf16 v[122:125], v[178:181], v[186:189], v[122:125]
	v_mfma_f32_16x16x32_bf16 v[118:121], v[170:173], v[196:199], v[118:121]
	v_mfma_f32_16x16x32_bf16 v[114:117], v[178:181], v[196:199], v[114:117]
	v_mfma_f32_16x16x32_bf16 v[110:113], v[170:173], v[204:207], v[110:113]
	v_mfma_f32_16x16x32_bf16 v[106:109], v[178:181], v[204:207], v[106:109]
	v_mfma_f32_16x16x32_bf16 v[102:105], v[170:173], v[212:215], v[102:105]
	v_mfma_f32_16x16x32_bf16 v[98:101], v[178:181], v[212:215], v[98:101]
	s_barrier
	s_setprio 0
	ds_read_b128 v[216:219], v143
	ds_read_b128 v[220:223], v143 offset:1024
	ds_read_b128 v[224:227], v143 offset:2048
	ds_read_b128 v[228:231], v143 offset:3072
	s_add_u32 s26, s19, 0x5c00180
	s_addc_u32 s27, s24, 0
	s_add_u32 m0, s98, 0x18000
	global_load_lds_dwordx4 v132, s[26:27]
	s_add_u32 m0, s98, 0x1a000
	global_load_lds_dwordx4 v130, s[26:27]
	s_setprio 1
	s_barrier
	s_waitcnt lgkmcnt(0)
	v_mfma_f32_16x16x32_bf16 v[94:97], v[216:219], v[182:185], v[94:97]
	v_mfma_f32_16x16x32_bf16 v[90:93], v[224:227], v[182:185], v[90:93]
	v_mfma_f32_16x16x32_bf16 v[86:89], v[216:219], v[190:193], v[86:89]
	v_mfma_f32_16x16x32_bf16 v[82:85], v[224:227], v[190:193], v[82:85]
	v_mfma_f32_16x16x32_bf16 v[78:81], v[216:219], v[200:203], v[78:81]
	v_mfma_f32_16x16x32_bf16 v[74:77], v[224:227], v[200:203], v[74:77]
	v_mfma_f32_16x16x32_bf16 v[70:73], v[216:219], v[208:211], v[70:73]
	v_mfma_f32_16x16x32_bf16 v[66:69], v[224:227], v[208:211], v[66:69]
	v_mfma_f32_16x16x32_bf16 v[94:97], v[220:223], v[186:189], v[94:97]
	v_mfma_f32_16x16x32_bf16 v[90:93], v[228:231], v[186:189], v[90:93]
	v_mfma_f32_16x16x32_bf16 v[86:89], v[220:223], v[196:199], v[86:89]
	v_mfma_f32_16x16x32_bf16 v[82:85], v[228:231], v[196:199], v[82:85]
	v_mfma_f32_16x16x32_bf16 v[78:81], v[220:223], v[204:207], v[78:81]
	v_mfma_f32_16x16x32_bf16 v[74:77], v[228:231], v[204:207], v[74:77]
	v_mfma_f32_16x16x32_bf16 v[70:73], v[220:223], v[212:215], v[70:73]
	v_mfma_f32_16x16x32_bf16 v[66:69], v[228:231], v[212:215], v[66:69]
	s_barrier
	s_setprio 0
	ds_read_b128 v[182:185], v141 offset:49152
	ds_read_b128 v[186:189], v141 offset:50176
	ds_read_b128 v[190:193], v139 offset:49152
	ds_read_b128 v[196:199], v139 offset:50176
	ds_read_b128 v[200:203], v137 offset:49152
	ds_read_b128 v[204:207], v137 offset:50176
	ds_read_b128 v[208:211], v135 offset:49152
	ds_read_b128 v[212:215], v135 offset:50176
	s_add_u32 s26, s15, 0x10000180
	s_addc_u32 s27, s18, 0
	s_add_u32 m0, s98, 0x8000
	global_load_lds_dwordx4 v132, s[26:27]
	s_add_u32 m0, s98, 0xa000
	global_load_lds_dwordx4 v130, s[26:27]
	s_setprio 1
	s_barrier
;   #define LDA(dst,b,h) for(int m=0;m<4;++m)for(int k=0;k<2;++k) \
;     dst[m][k]=*reinterpret_cast<const bf16x8*>((char*)SA(b,h)+lds_byte(wr*64+m*16+fr,k*32+fq*8))
;   #define LDB(dst,b,h) for(int n=0;n<2;++n)for(int k=0;k<2;++k) \
;     dst[n][k]=*reinterpret_cast<const bf16x8*>((char*)SB(b,h)+lds_byte(wc*32+n*16+fr,k*32+fq*8))
;   #define MMA(ai,bj,At,Bt_) do{__builtin_amdgcn_s_setprio(1); \
;     for(int m=0;m<4;++m)for(int n=0;n<2;++n)for(int k=0;k<2;++k) \
;       acc[ai][bj][m][n]=__builtin_amdgcn_mfma_f32_16x16x32_bf16(Bt_[n][k],At[m][k],acc[ai][bj][m][n],0,0,0); \
;     __builtin_amdgcn_s_setprio(0);}while(0)
;   #define WAIT_V(n) asm volatile("s_waitcnt vmcnt(" #n ")":::"memory")
;   #define WAIT_L(n) asm volatile("s_waitcnt lgkmcnt(" #n ")":::"memory")
;   #define BAR __builtin_amdgcn_s_barrier()
;   #define SCHED __builtin_amdgcn_sched_barrier(0)
; template <bool TWO, class MID> ...
;     ...
;     BAR; WAIT_L(0); MMA(1,0,At,B0); BAR; SCHED;
;     STAGE_B(SB(1,1),1,t+3);
;     WAIT_V(6); BAR; MMA(1,1,At,B1); BAR;
;   }
;   { LDB(B0,0,0); LDA(At,0,0); STAGE_A(SA(1,1),1,nt-1);
;     BAR; WAIT_L(0); MMA(0,0,At,B0); BAR;
;     LDB(B1,0,1); BAR; WAIT_L(0); MMA(0,1,At,B1); BAR;
;     LDA(At,0,1); WAIT_V(4); BAR; WAIT_L(0); MMA(1,0,At,B0); MMA(1,1,At,B1); BAR; }
	s_waitcnt lgkmcnt(0)
	v_mfma_f32_16x16x32_bf16 v[62:65], v[166:169], v[182:185], v[62:65]
	v_mfma_f32_16x16x32_bf16 v[58:61], v[174:177], v[182:185], v[58:61]
	v_mfma_f32_16x16x32_bf16 v[54:57], v[166:169], v[190:193], v[54:57]
	v_mfma_f32_16x16x32_bf16 v[50:53], v[174:177], v[190:193], v[50:53]
	v_mfma_f32_16x16x32_bf16 v[46:49], v[166:169], v[200:203], v[46:49]
	v_mfma_f32_16x16x32_bf16 v[42:45], v[174:177], v[200:203], v[42:45]
	v_mfma_f32_16x16x32_bf16 v[38:41], v[166:169], v[208:211], v[38:41]
	v_mfma_f32_16x16x32_bf16 v[34:37], v[174:177], v[208:211], v[34:37]
	v_mfma_f32_16x16x32_bf16 v[62:65], v[170:173], v[186:189], v[62:65]
	v_mfma_f32_16x16x32_bf16 v[58:61], v[178:181], v[186:189], v[58:61]
	v_mfma_f32_16x16x32_bf16 v[54:57], v[170:173], v[196:199], v[54:57]
	v_mfma_f32_16x16x32_bf16 v[50:53], v[178:181], v[196:199], v[50:53]
	v_mfma_f32_16x16x32_bf16 v[46:49], v[170:173], v[204:207], v[46:49]
	v_mfma_f32_16x16x32_bf16 v[42:45], v[178:181], v[204:207], v[42:45]
	v_mfma_f32_16x16x32_bf16 v[38:41], v[170:173], v[212:215], v[38:41]
	v_mfma_f32_16x16x32_bf16 v[34:37], v[178:181], v[212:215], v[34:37]
	s_barrier
	s_setprio 0
	s_add_u32 s18, s19, 0x5e00180
	s_addc_u32 s19, s24, 0
	s_add_u32 m0, s98, 0x1c000
	global_load_lds_dwordx4 v132, s[18:19]
	s_add_u32 m0, s98, 0x1e000
	global_load_lds_dwordx4 v130, s[18:19]
	s_waitcnt vmcnt(6)
	s_setprio 1
	s_barrier
	v_mfma_f32_16x16x32_bf16 v[30:33], v[216:219], v[182:185], v[30:33]
	v_mfma_f32_16x16x32_bf16 v[26:29], v[224:227], v[182:185], v[26:29]
	v_mfma_f32_16x16x32_bf16 v[22:25], v[216:219], v[190:193], v[22:25]
	v_mfma_f32_16x16x32_bf16 v[18:21], v[224:227], v[190:193], v[18:21]
	v_mfma_f32_16x16x32_bf16 v[14:17], v[216:219], v[200:203], v[14:17]
	v_mfma_f32_16x16x32_bf16 v[10:13], v[224:227], v[200:203], v[10:13]
	v_mfma_f32_16x16x32_bf16 v[6:9], v[216:219], v[208:211], v[6:9]
	v_mfma_f32_16x16x32_bf16 v[2:5], v[224:227], v[208:211], v[2:5]
	v_mfma_f32_16x16x32_bf16 v[30:33], v[220:223], v[186:189], v[30:33]
	v_mfma_f32_16x16x32_bf16 v[26:29], v[228:231], v[186:189], v[26:29]
	v_mfma_f32_16x16x32_bf16 v[22:25], v[220:223], v[196:199], v[22:25]
	v_mfma_f32_16x16x32_bf16 v[18:21], v[228:231], v[196:199], v[18:21]
	v_mfma_f32_16x16x32_bf16 v[14:17], v[220:223], v[204:207], v[14:17]
	v_mfma_f32_16x16x32_bf16 v[10:13], v[228:231], v[204:207], v[10:13]
	v_mfma_f32_16x16x32_bf16 v[6:9], v[220:223], v[212:215], v[6:9]
	v_mfma_f32_16x16x32_bf16 v[2:5], v[228:231], v[212:215], v[2:5]
	s_setprio 0
	s_add_i32 s14, s14, 2
	s_add_u32 s0, s0, 0x100
	s_addc_u32 s1, s1, 0
	s_cmpk_lt_u32 s14, 0x7c
	s_barrier
	s_cbranch_scc1 .LBB0_620
	ds_read_b128 v[152:155], v149
	ds_read_b128 v[156:159], v149 offset:1024
	ds_read_b128 v[160:163], v149 offset:2048
	ds_read_b128 v[164:167], v149 offset:3072
	ds_read_b128 v[168:171], v141
	ds_read_b128 v[172:175], v141 offset:1024
	ds_read_b128 v[176:179], v139
	ds_read_b128 v[180:183], v139 offset:1024
	ds_read_b128 v[184:187], v137
	ds_read_b128 v[188:191], v137 offset:1024
	ds_read_b128 v[196:199], v135
	ds_read_b128 v[200:203], v135 offset:1024
	s_add_u32 s0, s12, 0x203f80
	s_addc_u32 s1, s13, 0
	v_lshl_add_u64 v[132:133], s[0:1], 0, v[132:133]
	v_readfirstlane_b32 s12, v148
	s_mov_b32 m0, s12
	global_load_lds_dwordx4 v[132:133], off
	v_lshl_add_u64 v[130:131], s[0:1], 0, v[130:131]
	v_readfirstlane_b32 s0, v150
	s_mov_b32 m0, s0
	global_load_lds_dwordx4 v[130:131], off
	s_setprio 1
	s_barrier
	s_waitcnt lgkmcnt(0)
	v_mfma_f32_16x16x32_bf16 v[126:129], v[152:155], v[168:171], v[126:129]
	v_mfma_f32_16x16x32_bf16 v[122:125], v[160:163], v[168:171], v[122:125]
	v_mfma_f32_16x16x32_bf16 v[118:121], v[152:155], v[176:179], v[118:121]
	v_mfma_f32_16x16x32_bf16 v[114:117], v[160:163], v[176:179], v[114:117]
	v_mfma_f32_16x16x32_bf16 v[102:105], v[152:155], v[196:199], v[102:105]
	v_mfma_f32_16x16x32_bf16 v[98:101], v[160:163], v[196:199], v[98:101]
	v_mfma_f32_16x16x32_bf16 v[126:129], v[156:159], v[172:175], v[126:129]
	v_mfma_f32_16x16x32_bf16 v[122:125], v[164:167], v[172:175], v[122:125]
	v_mfma_f32_16x16x32_bf16 v[118:121], v[156:159], v[180:183], v[118:121]
	v_mfma_f32_16x16x32_bf16 v[114:117], v[164:167], v[180:183], v[114:117]
	v_mfma_f32_16x16x32_bf16 v[110:113], v[152:155], v[184:187], v[110:113]
	v_mfma_f32_16x16x32_bf16 v[106:109], v[160:163], v[184:187], v[106:109]
	v_mfma_f32_16x16x32_bf16 v[102:105], v[156:159], v[200:203], v[102:105]
	v_mfma_f32_16x16x32_bf16 v[98:101], v[164:167], v[200:203], v[98:101]
	v_mfma_f32_16x16x32_bf16 v[130:133], v[156:159], v[188:191], v[110:113]
	v_mfma_f32_16x16x32_bf16 v[148:151], v[164:167], v[188:191], v[106:109]
	s_barrier
	s_setprio 0
	s_nop 0
	ds_read_b128 v[106:109], v147
	ds_read_b128 v[110:113], v147 offset:1024
	ds_read_b128 v[204:207], v147 offset:2048
	ds_read_b128 v[208:211], v147 offset:3072
	s_setprio 1
	s_barrier
	s_waitcnt lgkmcnt(0)
	v_mfma_f32_16x16x32_bf16 v[86:89], v[106:109], v[176:179], v[86:89]
	v_mfma_f32_16x16x32_bf16 v[82:85], v[204:207], v[176:179], v[82:85]
	v_mfma_f32_16x16x32_bf16 v[70:73], v[106:109], v[196:199], v[70:73]
	v_mfma_f32_16x16x32_bf16 v[66:69], v[204:207], v[196:199], v[66:69]
	v_mfma_f32_16x16x32_bf16 v[94:97], v[106:109], v[168:171], v[94:97]
	v_mfma_f32_16x16x32_bf16 v[90:93], v[204:207], v[168:171], v[90:93]
	v_mfma_f32_16x16x32_bf16 v[86:89], v[110:113], v[180:183], v[86:89]
	v_mfma_f32_16x16x32_bf16 v[82:85], v[208:211], v[180:183], v[82:85]
	v_mfma_f32_16x16x32_bf16 v[78:81], v[106:109], v[184:187], v[78:81]
	v_mfma_f32_16x16x32_bf16 v[74:77], v[204:207], v[184:187], v[74:77]
	v_mfma_f32_16x16x32_bf16 v[70:73], v[110:113], v[200:203], v[70:73]
	v_mfma_f32_16x16x32_bf16 v[66:69], v[208:211], v[200:203], v[66:69]
	v_mfma_f32_16x16x32_bf16 v[212:215], v[110:113], v[172:175], v[94:97]
	v_mfma_f32_16x16x32_bf16 v[168:171], v[208:211], v[172:175], v[90:93]
	v_mfma_f32_16x16x32_bf16 v[172:175], v[110:113], v[188:191], v[78:81]
	v_mfma_f32_16x16x32_bf16 v[176:179], v[208:211], v[188:191], v[74:77]
	s_barrier
;   #define LDA(dst,b,h) for(int m=0;m<4;++m)for(int k=0;k<2;++k) \
;     dst[m][k]=*reinterpret_cast<const bf16x8*>((char*)SA(b,h)+lds_byte(wr*64+m*16+fr,k*32+fq*8))
;   #define LDB(dst,b,h) for(int n=0;n<2;++n)for(int k=0;k<2;++k) \
;     dst[n][k]=*reinterpret_cast<const bf16x8*>((char*)SB(b,h)+lds_byte(wc*32+n*16+fr,k*32+fq*8))
;   #define MMA(ai,bj,At,Bt_) do{__builtin_amdgcn_s_setprio(1); \
;     for(int m=0;m<4;++m)for(int n=0;n<2;++n)for(int k=0;k<2;++k) \
;       acc[ai][bj][m][n]=__builtin_amdgcn_mfma_f32_16x16x32_bf16(Bt_[n][k],At[m][k],acc[ai][bj][m][n],0,0,0); \
;     __builtin_amdgcn_s_setprio(0);}while(0)
;   #define WAIT_V(n) asm volatile("s_waitcnt vmcnt(" #n ")":::"memory")
;   #define WAIT_L(n) asm volatile("s_waitcnt lgkmcnt(" #n ")":::"memory")
;   #define BAR __builtin_amdgcn_s_barrier()
; template <bool TWO, class MID> ...
;     ...
;     LDA(At,0,1); WAIT_V(4); BAR; WAIT_L(0); MMA(1,0,At,B0); MMA(1,1,At,B1); BAR; }
;   { LDB(B0,1,0); LDA(At,1,0); WAIT_V(2); BAR; WAIT_L(0); MMA(0,0,At,B0); BAR;
	s_setprio 0
	s_nop 0
	ds_read_b128 v[74:77], v141 offset:16384
	ds_read_b128 v[78:81], v141 offset:17408
	ds_read_b128 v[90:93], v139 offset:16384
	ds_read_b128 v[94:97], v139 offset:17408
	ds_read_b128 v[180:183], v137 offset:16384
	ds_read_b128 v[184:187], v137 offset:17408
	ds_read_b128 v[188:191], v135 offset:16384
	ds_read_b128 v[196:199], v135 offset:17408
	s_waitcnt vmcnt(4)
	s_setprio 1
	s_barrier
	s_waitcnt lgkmcnt(0)
	v_mfma_f32_16x16x32_bf16 v[62:65], v[152:155], v[74:77], v[62:65]
	v_mfma_f32_16x16x32_bf16 v[58:61], v[160:163], v[74:77], v[58:61]
	v_mfma_f32_16x16x32_bf16 v[54:57], v[152:155], v[90:93], v[54:57]
	v_mfma_f32_16x16x32_bf16 v[50:53], v[160:163], v[90:93], v[50:53]
	v_mfma_f32_16x16x32_bf16 v[38:41], v[152:155], v[188:191], v[38:41]
	v_mfma_f32_16x16x32_bf16 v[34:37], v[160:163], v[188:191], v[34:37]
	v_mfma_f32_16x16x32_bf16 v[62:65], v[156:159], v[78:81], v[62:65]
	v_mfma_f32_16x16x32_bf16 v[58:61], v[164:167], v[78:81], v[58:61]
	v_mfma_f32_16x16x32_bf16 v[54:57], v[156:159], v[94:97], v[54:57]
	v_mfma_f32_16x16x32_bf16 v[50:53], v[164:167], v[94:97], v[50:53]
	v_mfma_f32_16x16x32_bf16 v[46:49], v[152:155], v[180:183], v[46:49]
	v_mfma_f32_16x16x32_bf16 v[42:45], v[160:163], v[180:183], v[42:45]
	v_mfma_f32_16x16x32_bf16 v[38:41], v[156:159], v[196:199], v[38:41]
	v_mfma_f32_16x16x32_bf16 v[34:37], v[164:167], v[196:199], v[34:37]
	v_mfma_f32_16x16x32_bf16 v[200:203], v[156:159], v[184:187], v[46:49]
	v_mfma_f32_16x16x32_bf16 v[216:219], v[164:167], v[184:187], v[42:45]
	s_setprio 0
	s_setprio 1
	v_mfma_f32_16x16x32_bf16 v[22:25], v[106:109], v[90:93], v[22:25]
	v_mfma_f32_16x16x32_bf16 v[18:21], v[204:207], v[90:93], v[18:21]
	v_mfma_f32_16x16x32_bf16 v[6:9], v[106:109], v[188:191], v[6:9]
	v_mfma_f32_16x16x32_bf16 v[2:5], v[204:207], v[188:191], v[2:5]
	v_mfma_f32_16x16x32_bf16 v[30:33], v[106:109], v[74:77], v[30:33]
	v_mfma_f32_16x16x32_bf16 v[26:29], v[204:207], v[74:77], v[26:29]
	v_mfma_f32_16x16x32_bf16 v[22:25], v[110:113], v[94:97], v[22:25]
	v_mfma_f32_16x16x32_bf16 v[18:21], v[208:211], v[94:97], v[18:21]
	v_mfma_f32_16x16x32_bf16 v[14:17], v[106:109], v[180:183], v[14:17]
	v_mfma_f32_16x16x32_bf16 v[10:13], v[204:207], v[180:183], v[10:13]
	v_mfma_f32_16x16x32_bf16 v[6:9], v[110:113], v[196:199], v[6:9]
	v_mfma_f32_16x16x32_bf16 v[2:5], v[208:211], v[196:199], v[2:5]
	v_mfma_f32_16x16x32_bf16 v[152:155], v[110:113], v[78:81], v[30:33]
	v_mfma_f32_16x16x32_bf16 v[156:159], v[208:211], v[78:81], v[26:29]
	v_mfma_f32_16x16x32_bf16 v[160:163], v[110:113], v[184:187], v[14:17]
	v_mfma_f32_16x16x32_bf16 v[164:167], v[208:211], v[184:187], v[10:13]
	s_barrier
	s_setprio 0
	s_nop 0
	ds_read_b128 v[10:13], v145
	ds_read_b128 v[14:17], v145 offset:1024
	ds_read_b128 v[180:183], v145 offset:2048
	ds_read_b128 v[144:147], v145 offset:3072
	ds_read_b128 v[26:29], v141 offset:32768
	ds_read_b128 v[30:33], v141 offset:33792
	ds_read_b128 v[42:45], v139 offset:32768
	ds_read_b128 v[46:49], v139 offset:33792
	ds_read_b128 v[184:187], v137 offset:32768
	ds_read_b128 v[188:191], v137 offset:33792
	ds_read_b128 v[196:199], v135 offset:32768
	ds_read_b128 v[204:207], v135 offset:33792
	s_waitcnt vmcnt(2)
	s_setprio 1
	s_barrier
	s_waitcnt lgkmcnt(0)
	v_mfma_f32_16x16x32_bf16 v[74:77], v[10:13], v[26:29], v[126:129]
	v_mfma_f32_16x16x32_bf16 v[126:129], v[14:17], v[30:33], v[74:77]
	v_mfma_f32_16x16x32_bf16 v[74:77], v[180:183], v[26:29], v[122:125]
	v_mfma_f32_16x16x32_bf16 v[122:125], v[144:147], v[30:33], v[74:77]
	v_mfma_f32_16x16x32_bf16 v[74:77], v[10:13], v[42:45], v[118:121]
	v_mfma_f32_16x16x32_bf16 v[110:113], v[14:17], v[46:49], v[74:77]
	v_mfma_f32_16x16x32_bf16 v[74:77], v[180:183], v[42:45], v[114:117]
	v_mfma_f32_16x16x32_bf16 v[106:109], v[144:147], v[46:49], v[74:77]
	v_mfma_f32_16x16x32_bf16 v[74:77], v[10:13], v[184:187], v[130:133]
	v_mfma_f32_16x16x32_bf16 v[94:97], v[14:17], v[188:191], v[74:77]
	v_mfma_f32_16x16x32_bf16 v[74:77], v[180:183], v[184:187], v[148:151]
	v_mfma_f32_16x16x32_bf16 v[90:93], v[144:147], v[188:191], v[74:77]
	v_mfma_f32_16x16x32_bf16 v[74:77], v[10:13], v[196:199], v[102:105]
	v_mfma_f32_16x16x32_bf16 v[78:81], v[14:17], v[204:207], v[74:77]
	v_mfma_f32_16x16x32_bf16 v[74:77], v[180:183], v[196:199], v[98:101]
	v_mfma_f32_16x16x32_bf16 v[74:77], v[144:147], v[204:207], v[74:77]
	s_barrier
;   #define LDA(dst,b,h) for(int m=0;m<4;++m)for(int k=0;k<2;++k) \
;     dst[m][k]=*reinterpret_cast<const bf16x8*>((char*)SA(b,h)+lds_byte(wr*64+m*16+fr,k*32+fq*8))
;   #define LDB(dst,b,h) for(int n=0;n<2;++n)for(int k=0;k<2;++k) \
;     dst[n][k]=*reinterpret_cast<const bf16x8*>((char*)SB(b,h)+lds_byte(wc*32+n*16+fr,k*32+fq*8))
;   #define MMA(ai,bj,At,Bt_) do{__builtin_amdgcn_s_setprio(1); \
;     for(int m=0;m<4;++m)for(int n=0;n<2;++n)for(int k=0;k<2;++k) \
;       acc[ai][bj][m][n]=__builtin_amdgcn_mfma_f32_16x16x32_bf16(Bt_[n][k],At[m][k],acc[ai][bj][m][n],0,0,0); \
;     __builtin_amdgcn_s_setprio(0);}while(0)
;   #define WAIT_V(n) asm volatile("s_waitcnt vmcnt(" #n ")":::"memory")
;   #define WAIT_L(n) asm volatile("s_waitcnt lgkmcnt(" #n ")":::"memory")
;   #define BAR __builtin_amdgcn_s_barrier()
; template <bool TWO, class MID> ...
;     ...
;     LDB(B1,1,1); WAIT_V(0); BAR; WAIT_L(0); MMA(0,1,At,B1); BAR;
;     LDA(At,1,1); BAR; WAIT_L(0); MMA(1,0,At,B0); MMA(1,1,At,B1); BAR; }
;   if(wr==0)BAR;
	s_setprio 0
	ds_read_b128 v[130:133], v143
	ds_read_b128 v[148:151], v143 offset:1024
	ds_read_b128 v[208:211], v143 offset:2048
	ds_read_b128 v[220:223], v143 offset:3072
	s_waitcnt vmcnt(0)
	s_setprio 1
	s_barrier
	s_waitcnt lgkmcnt(0)
	v_mfma_f32_16x16x32_bf16 v[98:101], v[130:133], v[26:29], v[212:215]
	v_mfma_f32_16x16x32_bf16 v[26:29], v[208:211], v[26:29], v[168:171]
	v_mfma_f32_16x16x32_bf16 v[114:117], v[220:223], v[30:33], v[26:29]
	v_mfma_f32_16x16x32_bf16 v[26:29], v[130:133], v[42:45], v[86:89]
	v_mfma_f32_16x16x32_bf16 v[102:105], v[148:151], v[46:49], v[26:29]
	v_mfma_f32_16x16x32_bf16 v[26:29], v[208:211], v[42:45], v[82:85]
	v_mfma_f32_16x16x32_bf16 v[118:121], v[148:151], v[30:33], v[98:101]
	v_mfma_f32_16x16x32_bf16 v[98:101], v[220:223], v[46:49], v[26:29]
	v_mfma_f32_16x16x32_bf16 v[26:29], v[130:133], v[184:187], v[172:175]
	v_mfma_f32_16x16x32_bf16 v[86:89], v[148:151], v[188:191], v[26:29]
	v_mfma_f32_16x16x32_bf16 v[26:29], v[208:211], v[184:187], v[176:179]
	v_mfma_f32_16x16x32_bf16 v[82:85], v[220:223], v[188:191], v[26:29]
	v_mfma_f32_16x16x32_bf16 v[26:29], v[130:133], v[196:199], v[70:73]
	v_mfma_f32_16x16x32_bf16 v[70:73], v[148:151], v[204:207], v[26:29]
	v_mfma_f32_16x16x32_bf16 v[26:29], v[208:211], v[196:199], v[66:69]
	v_mfma_f32_16x16x32_bf16 v[66:69], v[220:223], v[204:207], v[26:29]
	s_barrier
	s_setprio 0
	ds_read_b128 v[168:171], v141 offset:49152
	ds_read_b128 v[140:143], v141 offset:50176
	ds_read_b128 v[172:175], v139 offset:49152
	ds_read_b128 v[176:179], v139 offset:50176
	ds_read_b128 v[184:187], v137 offset:49152
	ds_read_b128 v[136:139], v137 offset:50176
	ds_read_b128 v[188:191], v135 offset:49152
	ds_read_b128 v[196:199], v135 offset:50176
	s_setprio 1
	s_barrier
	s_waitcnt lgkmcnt(0)
	v_mfma_f32_16x16x32_bf16 v[26:29], v[10:13], v[168:171], v[62:65]
	v_mfma_f32_16x16x32_bf16 v[62:65], v[14:17], v[140:143], v[26:29]
	v_mfma_f32_16x16x32_bf16 v[26:29], v[180:183], v[168:171], v[58:61]
	v_mfma_f32_16x16x32_bf16 v[58:61], v[144:147], v[140:143], v[26:29]
	v_mfma_f32_16x16x32_bf16 v[26:29], v[10:13], v[172:175], v[54:57]
	v_mfma_f32_16x16x32_bf16 v[46:49], v[14:17], v[176:179], v[26:29]
	v_mfma_f32_16x16x32_bf16 v[26:29], v[180:183], v[172:175], v[50:53]
	v_mfma_f32_16x16x32_bf16 v[42:45], v[144:147], v[176:179], v[26:29]
	v_mfma_f32_16x16x32_bf16 v[26:29], v[10:13], v[184:187], v[200:203]
	v_mfma_f32_16x16x32_bf16 v[10:13], v[10:13], v[188:191], v[38:41]
	v_mfma_f32_16x16x32_bf16 v[30:33], v[14:17], v[136:139], v[26:29]
	v_mfma_f32_16x16x32_bf16 v[26:29], v[180:183], v[184:187], v[216:219]
	v_mfma_f32_16x16x32_bf16 v[14:17], v[14:17], v[196:199], v[10:13]
	v_mfma_f32_16x16x32_bf16 v[10:13], v[180:183], v[188:191], v[34:37]
	v_mfma_f32_16x16x32_bf16 v[26:29], v[144:147], v[136:139], v[26:29]
	v_mfma_f32_16x16x32_bf16 v[10:13], v[144:147], v[196:199], v[10:13]
	s_setprio 0
	s_setprio 1
	v_mfma_f32_16x16x32_bf16 v[34:37], v[130:133], v[168:171], v[152:155]
	v_mfma_f32_16x16x32_bf16 v[54:57], v[148:151], v[140:143], v[34:37]
	v_mfma_f32_16x16x32_bf16 v[34:37], v[208:211], v[168:171], v[156:159]
	v_mfma_f32_16x16x32_bf16 v[18:21], v[208:211], v[172:175], v[18:21]
	v_mfma_f32_16x16x32_bf16 v[50:53], v[220:223], v[140:143], v[34:37]
	v_mfma_f32_16x16x32_bf16 v[22:25], v[130:133], v[172:175], v[22:25]
	v_mfma_f32_16x16x32_bf16 v[34:37], v[220:223], v[176:179], v[18:21]
	v_mfma_f32_16x16x32_bf16 v[18:21], v[130:133], v[184:187], v[160:163]
	v_mfma_f32_16x16x32_bf16 v[38:41], v[148:151], v[176:179], v[22:25]
	v_mfma_f32_16x16x32_bf16 v[22:25], v[148:151], v[136:139], v[18:21]
	v_mfma_f32_16x16x32_bf16 v[18:21], v[208:211], v[184:187], v[164:167]
	v_mfma_f32_16x16x32_bf16 v[6:9], v[130:133], v[188:191], v[6:9]
	v_mfma_f32_16x16x32_bf16 v[2:5], v[208:211], v[188:191], v[2:5]
	v_mfma_f32_16x16x32_bf16 v[18:21], v[220:223], v[136:139], v[18:21]
	v_mfma_f32_16x16x32_bf16 v[6:9], v[148:151], v[196:199], v[6:9]
	v_mfma_f32_16x16x32_bf16 v[2:5], v[220:223], v[196:199], v[2:5]
	s_setprio 0
	v_cmp_gt_u32_e32 vcc, s30, v1
	s_barrier
	s_and_saveexec_b64 s[0:1], vcc
	s_cbranch_execz .LBB0_623
	s_barrier
